# logits v3: coalesced row loads transposed through per-wave LDS staging, f32 MFMA 4x4x1
# baseline (speedup 1.0000x reference)
; __device__ __forceinline__ int opaque_tid() { int t = threadIdx.x; asm volatile("" : "+v"(t)); return t; }
; __global__ void __launch_bounds__(NWAVES * 64, 2) fwd_megakernel(Args args) {
;     ...
;             const int ln = opaque_tid() & 63;
;             float wreg[32];
; #pragma unroll
;             for (int jj = 0; jj < 4; ++jj) { const f32x4 a = *(const f32x4*)(wf + (size_t)wave * DM + 512 * jj + 8 * ln), bq = *(const f32x4*)(wf + (size_t)wave * DM + 512 * jj + 8 * ln + 4);
; #pragma unroll
;                 for (int e = 0; e < 4; ++e) { wreg[8 * jj + e] = a[e]; wreg[8 * jj + 4 + e] = bq[e]; } }
;             const float bf = args.in[8][wave];
;             for (int m0 = vcu2 * 4; m0 < M; m0 += G * 4) {
;                 u32x4 pw[4][4]; float sq[4];
; #pragma unroll
;                 for (int q = 0; q < 4; ++q) { sq[q] = ss[M + m0 + q];
; #pragma unroll
;                     for (int jj = 0; jj < 4; ++jj) pw[q][jj] = *(const u32x4*)(XB + (size_t)(m0 + q) * DM + 512 * jj + 8 * ln); }
.LBB0_591:
	s_and_b64 vcc, exec, s[4:5]
	s_cbranch_vccz .LBB0_605
	s_cmp_gt_i32 s39, 1
	s_cbranch_scc0 .LBB0_606
	s_cmp_lt_i32 s39, 3
	s_mov_b64 s[4:5], -1
	s_cbranch_scc0 .LBB0_607
	v_lshrrev_b32_e32 v0, 6, v166
	v_readlane_b32 s4, v249, 1
	v_readfirstlane_b32 s12, v0
	s_lshl_b32 s4, s4, 4
	s_cmpk_gt_i32 s4, 0x3fff
	s_cbranch_scc1 .Llg_done
	v_lshlrev_b32_e32 v0, 4, v166
	v_lshrrev_b32_e32 v4, 5, v166
	v_lshlrev_b32_e32 v4, 12, v4
	v_and_b32_e32 v5, 1, v166
	v_lshl_or_b32 v4, v5, 10, v4
	v_bfe_u32 v5, v166, 1, 4
	v_lshl_or_b32 v4, v5, 6, v4
	s_add_i32 s1, s12, 0
	s_and_b32 s1, s1, 7
	s_lshl_b32 s5, s1, 13
	s_add_u32 s5, s5, 0x100000
	s_add_u32 s8, s60, s5
	s_addc_u32 s9, s61, 0
	global_load_dwordx4 v[36:39], v0, s[8:9]
	s_add_i32 s1, s12, 1
	s_and_b32 s1, s1, 7
	s_lshl_b32 s5, s1, 13
	s_add_u32 s5, s5, 0x100000
	s_add_u32 s8, s60, s5
	s_addc_u32 s9, s61, 0
	global_load_dwordx4 v[40:43], v0, s[8:9]
	s_add_i32 s1, s12, 2
	s_and_b32 s1, s1, 7
	s_lshl_b32 s5, s1, 13
	s_add_u32 s5, s5, 0x100000
	s_add_u32 s8, s60, s5
	s_addc_u32 s9, s61, 0
	global_load_dwordx4 v[44:47], v0, s[8:9]
	s_add_i32 s1, s12, 3
	s_and_b32 s1, s1, 7
	s_lshl_b32 s5, s1, 13
	s_add_u32 s5, s5, 0x100000
	s_add_u32 s8, s60, s5
	s_addc_u32 s9, s61, 0
	global_load_dwordx4 v[48:51], v0, s[8:9]
	s_add_i32 s1, s12, 4
	s_and_b32 s1, s1, 7
	s_lshl_b32 s5, s1, 13
	s_add_u32 s5, s5, 0x100000
	s_add_u32 s8, s60, s5
	s_addc_u32 s9, s61, 0
	global_load_dwordx4 v[52:55], v0, s[8:9]
	s_add_i32 s1, s12, 5
	s_and_b32 s1, s1, 7
	s_lshl_b32 s5, s1, 13
	s_add_u32 s5, s5, 0x100000
	s_add_u32 s8, s60, s5
	s_addc_u32 s9, s61, 0
	global_load_dwordx4 v[56:59], v0, s[8:9]
	s_add_i32 s1, s12, 6
	s_and_b32 s1, s1, 7
	s_lshl_b32 s5, s1, 13
	s_add_u32 s5, s5, 0x100000
	s_add_u32 s8, s60, s5
	s_addc_u32 s9, s61, 0
	global_load_dwordx4 v[60:63], v0, s[8:9]
	s_add_i32 s1, s12, 7
	s_and_b32 s1, s1, 7
	s_lshl_b32 s5, s1, 13
	s_add_u32 s5, s5, 0x100000
	s_add_u32 s8, s60, s5
	s_addc_u32 s9, s61, 0
	global_load_dwordx4 v[64:67], v0, s[8:9]
	v_lshrrev_b32_e32 v5, 5, v168
	v_and_b32_e32 v6, 31, v168
	v_lshlrev_b32_e32 v7, 4, v6
	v_lshl_or_b32 v2, v5, 12, v7
	v_mul_u32_u24_e32 v5, 0x240, v5
	s_mul_i32 s5, s12, 0x1200
	s_add_u32 s5, s5, 0x10000
	v_add3_u32 v3, v5, v7, s5
	v_and_b32_e32 v5, 3, v168
	v_lshrrev_b32_e32 v6, 2, v168
	v_mul_u32_u24_e32 v5, 0x240, v5
	v_lshlrev_b32_e32 v6, 4, v6
	v_add3_u32 v116, v5, v6, s5
	v_lshlrev_b32_e32 v117, 4, v168
	v_readlane_b32 s16, v250, 63
	v_readlane_b32 s17, v249, 0
	s_lshl_b32 s5, s12, 2
	s_sub_u32 s16, s16, s5
	s_subb_u32 s17, s17, 0
	s_mov_b32 s18, 0xbfb8aa3b
	s_mov_b32 s19, 0x3f317218
	s_waitcnt vmcnt(7)
	s_add_i32 s1, s12, 0
	s_and_b32 s1, s1, 7
	s_lshr_b32 s5, s1, 2
	s_lshl_b32 s5, s5, 11
	s_and_b32 s1, s1, 3
	s_lshl_b32 s1, s1, 4
	s_add_u32 s5, s5, s1
	v_add_u32_e32 v5, s5, v4
	ds_write_b128 v5, v[36:39]
	s_waitcnt vmcnt(6)
	s_add_i32 s1, s12, 1
	s_and_b32 s1, s1, 7
	s_lshr_b32 s5, s1, 2
	s_lshl_b32 s5, s5, 11
	s_and_b32 s1, s1, 3
	s_lshl_b32 s1, s1, 4
	s_add_u32 s5, s5, s1
	v_add_u32_e32 v5, s5, v4
	ds_write_b128 v5, v[40:43]
	s_waitcnt vmcnt(5)
	s_add_i32 s1, s12, 2
	s_and_b32 s1, s1, 7
	s_lshr_b32 s5, s1, 2
	s_lshl_b32 s5, s5, 11
	s_and_b32 s1, s1, 3
	s_lshl_b32 s1, s1, 4
	s_add_u32 s5, s5, s1
	v_add_u32_e32 v5, s5, v4
	ds_write_b128 v5, v[44:47]
	s_waitcnt vmcnt(4)
	s_add_i32 s1, s12, 3
	s_and_b32 s1, s1, 7
	s_lshr_b32 s5, s1, 2
	s_lshl_b32 s5, s5, 11
	s_and_b32 s1, s1, 3
	s_lshl_b32 s1, s1, 4
	s_add_u32 s5, s5, s1
	v_add_u32_e32 v5, s5, v4
	ds_write_b128 v5, v[48:51]
	s_waitcnt vmcnt(3)
	s_add_i32 s1, s12, 4
	s_and_b32 s1, s1, 7
	s_lshr_b32 s5, s1, 2
	s_lshl_b32 s5, s5, 11
	s_and_b32 s1, s1, 3
	s_lshl_b32 s1, s1, 4
	s_add_u32 s5, s5, s1
	v_add_u32_e32 v5, s5, v4
	ds_write_b128 v5, v[52:55]
	s_waitcnt vmcnt(2)
	s_add_i32 s1, s12, 5
	s_and_b32 s1, s1, 7
	s_lshr_b32 s5, s1, 2
	s_lshl_b32 s5, s5, 11
	s_and_b32 s1, s1, 3
	s_lshl_b32 s1, s1, 4
	s_add_u32 s5, s5, s1
	v_add_u32_e32 v5, s5, v4
	ds_write_b128 v5, v[56:59]
	s_waitcnt vmcnt(1)
	s_add_i32 s1, s12, 6
	s_and_b32 s1, s1, 7
	s_lshr_b32 s5, s1, 2
	s_lshl_b32 s5, s5, 11
	s_and_b32 s1, s1, 3
	s_lshl_b32 s1, s1, 4
	s_add_u32 s5, s5, s1
	v_add_u32_e32 v5, s5, v4
	ds_write_b128 v5, v[60:63]
	s_waitcnt vmcnt(0)
	s_add_i32 s1, s12, 7
	s_and_b32 s1, s1, 7
	s_lshr_b32 s5, s1, 2
	s_lshl_b32 s5, s5, 11
	s_and_b32 s1, s1, 3
	s_lshl_b32 s1, s1, 4
	s_add_u32 s5, s5, s1
	v_add_u32_e32 v5, s5, v4
	ds_write_b128 v5, v[64:67]
	s_waitcnt lgkmcnt(0)
	s_barrier
; __global__ void __launch_bounds__(NWAVES * 64, 2) fwd_megakernel(Args args) {
;     ...
;             for (int m0 = vcu2 * 4; m0 < M; m0 += G * 4) {
;                 u32x4 pw[4][4]; float sq[4];
; #pragma unroll
;                 for (int q = 0; q < 4; ++q) { sq[q] = ss[M + m0 + q];
; #pragma unroll
;                     for (int jj = 0; jj < 4; ++jj) pw[q][jj] = *(const u32x4*)(XB + (size_t)(m0 + q) * DM + 512 * jj + 8 * ln); }
; #pragma unroll
;                 for (int q = 0; q < 4; ++q) { float d = 0.f;
; #pragma unroll
;                     for (int jj = 0; jj < 4; ++jj) { const u32x4 w = pw[q][jj];
;                         d += __uint_as_float(w.x << 16) * wreg[8 * jj + 0] + __uint_as_float(w.x & 0xffff0000u) * wreg[8 * jj + 1] + __uint_as_float(w.y << 16) * wreg[8 * jj + 2] + __uint_as_float(w.y & 0xffff0000u) * wreg[8 * jj + 3]
;                            + __uint_as_float(w.z << 16) * wreg[8 * jj + 4] + __uint_as_float(w.z & 0xffff0000u) * wreg[8 * jj + 5] + __uint_as_float(w.w << 16) * wreg[8 * jj + 6] + __uint_as_float(w.w & 0xffff0000u) * wreg[8 * jj + 7]; }
.Llg_trip:
	s_lshl_b32 s5, s12, 3
	s_add_u32 s5, s5, s4
	s_lshl_b32 s5, s5, 12
	s_add_u32 s6, s94, s5
	s_addc_u32 s7, s95, 0
	s_lshr_b32 s13, s4, 6
	s_add_i32 s13, s13, s12
	v_mov_b32_e32 v4, 0
	v_mov_b32_e32 v5, 0
	v_mov_b32_e32 v6, 0
	v_mov_b32_e32 v7, 0
	v_mov_b32_e32 v8, 0
	v_mov_b32_e32 v9, 0
	v_mov_b32_e32 v10, 0
	v_mov_b32_e32 v11, 0
	v_mov_b32_e32 v12, 0
	v_mov_b32_e32 v13, 0
	v_mov_b32_e32 v14, 0
	v_mov_b32_e32 v15, 0
	v_mov_b32_e32 v16, 0
	v_mov_b32_e32 v17, 0
	v_mov_b32_e32 v18, 0
	v_mov_b32_e32 v19, 0
	s_add_i32 s36, s13, 0
	s_and_b32 s36, s36, 7
	s_lshl_b32 s1, s36, 9
	s_add_u32 s10, s6, s1
	s_addc_u32 s11, s7, 0
	global_load_dwordx4 v[120:123], v2, s[10:11]
	s_add_u32 s10, s10, 0x2000
	s_addc_u32 s11, s11, 0
	global_load_dwordx4 v[124:127], v2, s[10:11]
	s_add_u32 s10, s10, 0x2000
	s_addc_u32 s11, s11, 0
	global_load_dwordx4 v[128:131], v2, s[10:11]
	s_add_u32 s10, s10, 0x2000
	s_addc_u32 s11, s11, 0
	global_load_dwordx4 v[132:135], v2, s[10:11]
	s_add_i32 s36, s13, 1
	s_and_b32 s36, s36, 7
	s_lshl_b32 s1, s36, 9
	s_add_u32 s10, s6, s1
	s_addc_u32 s11, s7, 0
	global_load_dwordx4 v[136:139], v2, s[10:11]
	s_add_u32 s10, s10, 0x2000
	s_addc_u32 s11, s11, 0
	global_load_dwordx4 v[140:143], v2, s[10:11]
	s_add_u32 s10, s10, 0x2000
	s_addc_u32 s11, s11, 0
	global_load_dwordx4 v[144:147], v2, s[10:11]
	s_add_u32 s10, s10, 0x2000
	s_addc_u32 s11, s11, 0
	global_load_dwordx4 v[148:151], v2, s[10:11]
	s_add_i32 s36, s13, 2
	s_and_b32 s36, s36, 7
	s_lshl_b32 s1, s36, 9
	s_add_u32 s10, s6, s1
	s_addc_u32 s11, s7, 0
	global_load_dwordx4 v[100:103], v2, s[10:11]
	s_add_u32 s10, s10, 0x2000
	s_addc_u32 s11, s11, 0
	global_load_dwordx4 v[104:107], v2, s[10:11]
	s_add_u32 s10, s10, 0x2000
	s_addc_u32 s11, s11, 0
	global_load_dwordx4 v[108:111], v2, s[10:11]
	s_add_u32 s10, s10, 0x2000
	s_addc_u32 s11, s11, 0
	global_load_dwordx4 v[112:115], v2, s[10:11]
	s_add_i32 s36, s13, 0
	s_and_b32 s36, s36, 7
	s_lshl_b32 s1, s36, 13
	v_add_u32_e32 v118, s1, v117
	ds_read_b128 v[68:71], v118 offset:0
	ds_read_b128 v[72:75], v118 offset:1024
	ds_read_b128 v[76:79], v118 offset:2048
	ds_read_b128 v[80:83], v118 offset:3072
	s_waitcnt vmcnt(8)
	ds_write_b128 v3, v[120:123] offset:0
	ds_write_b128 v3, v[124:127] offset:1152
	ds_write_b128 v3, v[128:131] offset:2304
	ds_write_b128 v3, v[132:135] offset:3456
	s_add_i32 s36, s13, 3
	s_and_b32 s36, s36, 7
	s_lshl_b32 s1, s36, 9
	s_add_u32 s10, s6, s1
	s_addc_u32 s11, s7, 0
	global_load_dwordx4 v[120:123], v2, s[10:11]
	s_add_u32 s10, s10, 0x2000
	s_addc_u32 s11, s11, 0
	global_load_dwordx4 v[124:127], v2, s[10:11]
	s_add_u32 s10, s10, 0x2000
	s_addc_u32 s11, s11, 0
	global_load_dwordx4 v[128:131], v2, s[10:11]
	s_add_u32 s10, s10, 0x2000
	s_addc_u32 s11, s11, 0
	global_load_dwordx4 v[132:135], v2, s[10:11]
	s_add_i32 s36, s13, 0
	s_and_b32 s36, s36, 7
	s_waitcnt lgkmcnt(0)
	ds_read_b128 v[36:39], v116 offset:0
	ds_read_b128 v[40:43], v116 offset:2304
	ds_read_b128 v[44:47], v116 offset:256
	ds_read_b128 v[48:51], v116 offset:2560
	s_lshl_b32 s1, s36, 13
	s_add_u32 s1, s1, 0x1000
	v_add_u32_e32 v118, s1, v117
	ds_read_b128 v[84:87], v118 offset:0
	ds_read_b128 v[88:91], v118 offset:1024
	ds_read_b128 v[92:95], v118 offset:2048
	ds_read_b128 v[96:99], v118 offset:3072
	s_waitcnt lgkmcnt(6)
	v_lshlrev_b32_e32 v20, 16, v36
	v_and_b32_e32 v36, 0xffff0000, v36
	v_lshlrev_b32_e32 v21, 16, v37
	v_and_b32_e32 v37, 0xffff0000, v37
	v_lshlrev_b32_e32 v22, 16, v38
	v_and_b32_e32 v38, 0xffff0000, v38
	v_lshlrev_b32_e32 v23, 16, v39
	v_and_b32_e32 v39, 0xffff0000, v39
	v_lshlrev_b32_e32 v24, 16, v40
	v_and_b32_e32 v40, 0xffff0000, v40
	v_lshlrev_b32_e32 v25, 16, v41
	v_and_b32_e32 v41, 0xffff0000, v41
	v_lshlrev_b32_e32 v26, 16, v42
	v_and_b32_e32 v42, 0xffff0000, v42
	v_lshlrev_b32_e32 v27, 16, v43
	v_and_b32_e32 v43, 0xffff0000, v43
	v_mfma_f32_4x4x1_16b_f32 v[4:7], v20, v68, v[4:7]
	v_mfma_f32_4x4x1_16b_f32 v[8:11], v20, v76, v[8:11]
	s_waitcnt lgkmcnt(4)
	v_mfma_f32_4x4x1_16b_f32 v[12:15], v24, v68, v[12:15]
	v_lshlrev_b32_e32 v28, 16, v44
	v_mfma_f32_4x4x1_16b_f32 v[16:19], v24, v76, v[16:19]
	v_mfma_f32_4x4x1_16b_f32 v[4:7], v36, v69, v[4:7]
	v_and_b32_e32 v44, 0xffff0000, v44
	v_mfma_f32_4x4x1_16b_f32 v[8:11], v36, v77, v[8:11]
	v_mfma_f32_4x4x1_16b_f32 v[12:15], v40, v69, v[12:15]
	v_lshlrev_b32_e32 v29, 16, v45
	v_mfma_f32_4x4x1_16b_f32 v[16:19], v40, v77, v[16:19]
	v_mfma_f32_4x4x1_16b_f32 v[4:7], v21, v70, v[4:7]
	v_and_b32_e32 v45, 0xffff0000, v45
	v_mfma_f32_4x4x1_16b_f32 v[8:11], v21, v78, v[8:11]
	v_mfma_f32_4x4x1_16b_f32 v[12:15], v25, v70, v[12:15]
	v_lshlrev_b32_e32 v30, 16, v46
	v_mfma_f32_4x4x1_16b_f32 v[16:19], v25, v78, v[16:19]
	v_mfma_f32_4x4x1_16b_f32 v[4:7], v37, v71, v[4:7]
	v_and_b32_e32 v46, 0xffff0000, v46
	v_mfma_f32_4x4x1_16b_f32 v[8:11], v37, v79, v[8:11]
	v_mfma_f32_4x4x1_16b_f32 v[12:15], v41, v71, v[12:15]
	v_lshlrev_b32_e32 v31, 16, v47
	v_mfma_f32_4x4x1_16b_f32 v[16:19], v41, v79, v[16:19]
	v_mfma_f32_4x4x1_16b_f32 v[4:7], v22, v72, v[4:7]
	v_and_b32_e32 v47, 0xffff0000, v47
	v_mfma_f32_4x4x1_16b_f32 v[8:11], v22, v80, v[8:11]
	v_mfma_f32_4x4x1_16b_f32 v[12:15], v26, v72, v[12:15]
	v_lshlrev_b32_e32 v32, 16, v48
	v_mfma_f32_4x4x1_16b_f32 v[16:19], v26, v80, v[16:19]
	v_mfma_f32_4x4x1_16b_f32 v[4:7], v38, v73, v[4:7]
	v_and_b32_e32 v48, 0xffff0000, v48
	v_mfma_f32_4x4x1_16b_f32 v[8:11], v38, v81, v[8:11]
	v_mfma_f32_4x4x1_16b_f32 v[12:15], v42, v73, v[12:15]
	v_lshlrev_b32_e32 v33, 16, v49
	v_mfma_f32_4x4x1_16b_f32 v[16:19], v42, v81, v[16:19]
	v_mfma_f32_4x4x1_16b_f32 v[4:7], v23, v74, v[4:7]
	v_and_b32_e32 v49, 0xffff0000, v49
	v_mfma_f32_4x4x1_16b_f32 v[8:11], v23, v82, v[8:11]
	v_mfma_f32_4x4x1_16b_f32 v[12:15], v27, v74, v[12:15]
	v_lshlrev_b32_e32 v34, 16, v50
	v_mfma_f32_4x4x1_16b_f32 v[16:19], v27, v82, v[16:19]
	v_mfma_f32_4x4x1_16b_f32 v[4:7], v39, v75, v[4:7]
	v_and_b32_e32 v50, 0xffff0000, v50
	v_mfma_f32_4x4x1_16b_f32 v[8:11], v39, v83, v[8:11]
	v_mfma_f32_4x4x1_16b_f32 v[12:15], v43, v75, v[12:15]
	v_lshlrev_b32_e32 v35, 16, v51
	v_mfma_f32_4x4x1_16b_f32 v[16:19], v43, v83, v[16:19]
	s_waitcnt lgkmcnt(0)
; __global__ void __launch_bounds__(NWAVES * 64, 2) fwd_megakernel(Args args) {
;     ...
;                     for (int jj = 0; jj < 4; ++jj) pw[q][jj] = *(const u32x4*)(XB + (size_t)(m0 + q) * DM + 512 * jj + 8 * ln); }
; #pragma unroll
;                 for (int q = 0; q < 4; ++q) { float d = 0.f;
; #pragma unroll
;                     for (int jj = 0; jj < 4; ++jj) { const u32x4 w = pw[q][jj];
;                         d += __uint_as_float(w.x << 16) * wreg[8 * jj + 0] + __uint_as_float(w.x & 0xffff0000u) * wreg[8 * jj + 1] + __uint_as_float(w.y << 16) * wreg[8 * jj + 2] + __uint_as_float(w.y & 0xffff0000u) * wreg[8 * jj + 3]
;                            + __uint_as_float(w.z << 16) * wreg[8 * jj + 4] + __uint_as_float(w.z & 0xffff0000u) * wreg[8 * jj + 5] + __uint_as_float(w.w << 16) * wreg[8 * jj + 6] + __uint_as_float(w.w & 0xffff0000u) * wreg[8 * jj + 7]; }
	v_mfma_f32_4x4x1_16b_f32 v[4:7], v28, v84, v[4:7]
	v_mfma_f32_4x4x1_16b_f32 v[8:11], v28, v92, v[8:11]
	v_mfma_f32_4x4x1_16b_f32 v[12:15], v32, v84, v[12:15]
	v_mfma_f32_4x4x1_16b_f32 v[16:19], v32, v92, v[16:19]
	v_mfma_f32_4x4x1_16b_f32 v[4:7], v44, v85, v[4:7]
	v_mfma_f32_4x4x1_16b_f32 v[8:11], v44, v93, v[8:11]
	v_mfma_f32_4x4x1_16b_f32 v[12:15], v48, v85, v[12:15]
	v_mfma_f32_4x4x1_16b_f32 v[16:19], v48, v93, v[16:19]
	v_mfma_f32_4x4x1_16b_f32 v[4:7], v29, v86, v[4:7]
	v_mfma_f32_4x4x1_16b_f32 v[8:11], v29, v94, v[8:11]
	v_mfma_f32_4x4x1_16b_f32 v[12:15], v33, v86, v[12:15]
	v_mfma_f32_4x4x1_16b_f32 v[16:19], v33, v94, v[16:19]
	v_mfma_f32_4x4x1_16b_f32 v[4:7], v45, v87, v[4:7]
	v_mfma_f32_4x4x1_16b_f32 v[8:11], v45, v95, v[8:11]
	v_mfma_f32_4x4x1_16b_f32 v[12:15], v49, v87, v[12:15]
	v_mfma_f32_4x4x1_16b_f32 v[16:19], v49, v95, v[16:19]
	v_mfma_f32_4x4x1_16b_f32 v[4:7], v30, v88, v[4:7]
	v_mfma_f32_4x4x1_16b_f32 v[8:11], v30, v96, v[8:11]
	v_mfma_f32_4x4x1_16b_f32 v[12:15], v34, v88, v[12:15]
	v_mfma_f32_4x4x1_16b_f32 v[16:19], v34, v96, v[16:19]
	v_mfma_f32_4x4x1_16b_f32 v[4:7], v46, v89, v[4:7]
	v_mfma_f32_4x4x1_16b_f32 v[8:11], v46, v97, v[8:11]
	v_mfma_f32_4x4x1_16b_f32 v[12:15], v50, v89, v[12:15]
	v_mfma_f32_4x4x1_16b_f32 v[16:19], v50, v97, v[16:19]
	v_mfma_f32_4x4x1_16b_f32 v[4:7], v31, v90, v[4:7]
	v_mfma_f32_4x4x1_16b_f32 v[8:11], v31, v98, v[8:11]
	v_mfma_f32_4x4x1_16b_f32 v[12:15], v35, v90, v[12:15]
	v_mfma_f32_4x4x1_16b_f32 v[16:19], v35, v98, v[16:19]
	v_mfma_f32_4x4x1_16b_f32 v[4:7], v47, v91, v[4:7]
	v_mfma_f32_4x4x1_16b_f32 v[8:11], v47, v99, v[8:11]
	v_mfma_f32_4x4x1_16b_f32 v[12:15], v51, v91, v[12:15]
	v_mfma_f32_4x4x1_16b_f32 v[16:19], v51, v99, v[16:19]
	s_add_i32 s36, s13, 1
	s_and_b32 s36, s36, 7
	s_lshl_b32 s1, s36, 13
	v_add_u32_e32 v118, s1, v117
	ds_read_b128 v[68:71], v118 offset:0
	ds_read_b128 v[72:75], v118 offset:1024
	ds_read_b128 v[76:79], v118 offset:2048
	ds_read_b128 v[80:83], v118 offset:3072
	s_waitcnt vmcnt(8)
	ds_write_b128 v3, v[136:139] offset:0
	ds_write_b128 v3, v[140:143] offset:1152
	ds_write_b128 v3, v[144:147] offset:2304
	ds_write_b128 v3, v[148:151] offset:3456
	s_add_i32 s36, s13, 4
	s_and_b32 s36, s36, 7
	s_lshl_b32 s1, s36, 9
	s_add_u32 s10, s6, s1
	s_addc_u32 s11, s7, 0
	global_load_dwordx4 v[136:139], v2, s[10:11]
	s_add_u32 s10, s10, 0x2000
	s_addc_u32 s11, s11, 0
	global_load_dwordx4 v[140:143], v2, s[10:11]
	s_add_u32 s10, s10, 0x2000
	s_addc_u32 s11, s11, 0
	global_load_dwordx4 v[144:147], v2, s[10:11]
	s_add_u32 s10, s10, 0x2000
	s_addc_u32 s11, s11, 0
	global_load_dwordx4 v[148:151], v2, s[10:11]
	s_add_i32 s36, s13, 1
	s_and_b32 s36, s36, 7
	s_waitcnt lgkmcnt(0)
	ds_read_b128 v[36:39], v116 offset:0
	ds_read_b128 v[40:43], v116 offset:2304
	ds_read_b128 v[44:47], v116 offset:256
	ds_read_b128 v[48:51], v116 offset:2560
	s_lshl_b32 s1, s36, 13
	s_add_u32 s1, s1, 0x1000
	v_add_u32_e32 v118, s1, v117
	ds_read_b128 v[84:87], v118 offset:0
	ds_read_b128 v[88:91], v118 offset:1024
	ds_read_b128 v[92:95], v118 offset:2048
	ds_read_b128 v[96:99], v118 offset:3072
	s_waitcnt lgkmcnt(6)
	v_lshlrev_b32_e32 v20, 16, v36
	v_and_b32_e32 v36, 0xffff0000, v36
	v_lshlrev_b32_e32 v21, 16, v37
	v_and_b32_e32 v37, 0xffff0000, v37
	v_lshlrev_b32_e32 v22, 16, v38
	v_and_b32_e32 v38, 0xffff0000, v38
	v_lshlrev_b32_e32 v23, 16, v39
	v_and_b32_e32 v39, 0xffff0000, v39
	v_lshlrev_b32_e32 v24, 16, v40
	v_and_b32_e32 v40, 0xffff0000, v40
	v_lshlrev_b32_e32 v25, 16, v41
	v_and_b32_e32 v41, 0xffff0000, v41
	v_lshlrev_b32_e32 v26, 16, v42
	v_and_b32_e32 v42, 0xffff0000, v42
	v_lshlrev_b32_e32 v27, 16, v43
	v_and_b32_e32 v43, 0xffff0000, v43
	v_mfma_f32_4x4x1_16b_f32 v[4:7], v20, v68, v[4:7]
	v_mfma_f32_4x4x1_16b_f32 v[8:11], v20, v76, v[8:11]
	s_waitcnt lgkmcnt(4)
	v_mfma_f32_4x4x1_16b_f32 v[12:15], v24, v68, v[12:15]
	v_lshlrev_b32_e32 v28, 16, v44
	v_mfma_f32_4x4x1_16b_f32 v[16:19], v24, v76, v[16:19]
	v_mfma_f32_4x4x1_16b_f32 v[4:7], v36, v69, v[4:7]
	v_and_b32_e32 v44, 0xffff0000, v44
	v_mfma_f32_4x4x1_16b_f32 v[8:11], v36, v77, v[8:11]
	v_mfma_f32_4x4x1_16b_f32 v[12:15], v40, v69, v[12:15]
	v_lshlrev_b32_e32 v29, 16, v45
	v_mfma_f32_4x4x1_16b_f32 v[16:19], v40, v77, v[16:19]
	v_mfma_f32_4x4x1_16b_f32 v[4:7], v21, v70, v[4:7]
	v_and_b32_e32 v45, 0xffff0000, v45
	v_mfma_f32_4x4x1_16b_f32 v[8:11], v21, v78, v[8:11]
	v_mfma_f32_4x4x1_16b_f32 v[12:15], v25, v70, v[12:15]
	v_lshlrev_b32_e32 v30, 16, v46
	v_mfma_f32_4x4x1_16b_f32 v[16:19], v25, v78, v[16:19]
	v_mfma_f32_4x4x1_16b_f32 v[4:7], v37, v71, v[4:7]
	v_and_b32_e32 v46, 0xffff0000, v46
	v_mfma_f32_4x4x1_16b_f32 v[8:11], v37, v79, v[8:11]
	v_mfma_f32_4x4x1_16b_f32 v[12:15], v41, v71, v[12:15]
	v_lshlrev_b32_e32 v31, 16, v47
	v_mfma_f32_4x4x1_16b_f32 v[16:19], v41, v79, v[16:19]
	v_mfma_f32_4x4x1_16b_f32 v[4:7], v22, v72, v[4:7]
	v_and_b32_e32 v47, 0xffff0000, v47
	v_mfma_f32_4x4x1_16b_f32 v[8:11], v22, v80, v[8:11]
	v_mfma_f32_4x4x1_16b_f32 v[12:15], v26, v72, v[12:15]
	v_lshlrev_b32_e32 v32, 16, v48
	v_mfma_f32_4x4x1_16b_f32 v[16:19], v26, v80, v[16:19]
	v_mfma_f32_4x4x1_16b_f32 v[4:7], v38, v73, v[4:7]
	v_and_b32_e32 v48, 0xffff0000, v48
	v_mfma_f32_4x4x1_16b_f32 v[8:11], v38, v81, v[8:11]
	v_mfma_f32_4x4x1_16b_f32 v[12:15], v42, v73, v[12:15]
	v_lshlrev_b32_e32 v33, 16, v49
	v_mfma_f32_4x4x1_16b_f32 v[16:19], v42, v81, v[16:19]
	v_mfma_f32_4x4x1_16b_f32 v[4:7], v23, v74, v[4:7]
	v_and_b32_e32 v49, 0xffff0000, v49
	v_mfma_f32_4x4x1_16b_f32 v[8:11], v23, v82, v[8:11]
	v_mfma_f32_4x4x1_16b_f32 v[12:15], v27, v74, v[12:15]
	v_lshlrev_b32_e32 v34, 16, v50
	v_mfma_f32_4x4x1_16b_f32 v[16:19], v27, v82, v[16:19]
	v_mfma_f32_4x4x1_16b_f32 v[4:7], v39, v75, v[4:7]
	v_and_b32_e32 v50, 0xffff0000, v50
	v_mfma_f32_4x4x1_16b_f32 v[8:11], v39, v83, v[8:11]
	v_mfma_f32_4x4x1_16b_f32 v[12:15], v43, v75, v[12:15]
	v_lshlrev_b32_e32 v35, 16, v51
	v_mfma_f32_4x4x1_16b_f32 v[16:19], v43, v83, v[16:19]
	s_waitcnt lgkmcnt(0)
; __global__ void __launch_bounds__(NWAVES * 64, 2) fwd_megakernel(Args args) {
;     ...
;                     for (int jj = 0; jj < 4; ++jj) pw[q][jj] = *(const u32x4*)(XB + (size_t)(m0 + q) * DM + 512 * jj + 8 * ln); }
; #pragma unroll
;                 for (int q = 0; q < 4; ++q) { float d = 0.f;
; #pragma unroll
;                     for (int jj = 0; jj < 4; ++jj) { const u32x4 w = pw[q][jj];
;                         d += __uint_as_float(w.x << 16) * wreg[8 * jj + 0] + __uint_as_float(w.x & 0xffff0000u) * wreg[8 * jj + 1] + __uint_as_float(w.y << 16) * wreg[8 * jj + 2] + __uint_as_float(w.y & 0xffff0000u) * wreg[8 * jj + 3]
;                            + __uint_as_float(w.z << 16) * wreg[8 * jj + 4] + __uint_as_float(w.z & 0xffff0000u) * wreg[8 * jj + 5] + __uint_as_float(w.w << 16) * wreg[8 * jj + 6] + __uint_as_float(w.w & 0xffff0000u) * wreg[8 * jj + 7]; }
	v_mfma_f32_4x4x1_16b_f32 v[4:7], v28, v84, v[4:7]
	v_mfma_f32_4x4x1_16b_f32 v[8:11], v28, v92, v[8:11]
	v_mfma_f32_4x4x1_16b_f32 v[12:15], v32, v84, v[12:15]
	v_mfma_f32_4x4x1_16b_f32 v[16:19], v32, v92, v[16:19]
	v_mfma_f32_4x4x1_16b_f32 v[4:7], v44, v85, v[4:7]
	v_mfma_f32_4x4x1_16b_f32 v[8:11], v44, v93, v[8:11]
	v_mfma_f32_4x4x1_16b_f32 v[12:15], v48, v85, v[12:15]
	v_mfma_f32_4x4x1_16b_f32 v[16:19], v48, v93, v[16:19]
	v_mfma_f32_4x4x1_16b_f32 v[4:7], v29, v86, v[4:7]
	v_mfma_f32_4x4x1_16b_f32 v[8:11], v29, v94, v[8:11]
	v_mfma_f32_4x4x1_16b_f32 v[12:15], v33, v86, v[12:15]
	v_mfma_f32_4x4x1_16b_f32 v[16:19], v33, v94, v[16:19]
	v_mfma_f32_4x4x1_16b_f32 v[4:7], v45, v87, v[4:7]
	v_mfma_f32_4x4x1_16b_f32 v[8:11], v45, v95, v[8:11]
	v_mfma_f32_4x4x1_16b_f32 v[12:15], v49, v87, v[12:15]
	v_mfma_f32_4x4x1_16b_f32 v[16:19], v49, v95, v[16:19]
	v_mfma_f32_4x4x1_16b_f32 v[4:7], v30, v88, v[4:7]
	v_mfma_f32_4x4x1_16b_f32 v[8:11], v30, v96, v[8:11]
	v_mfma_f32_4x4x1_16b_f32 v[12:15], v34, v88, v[12:15]
	v_mfma_f32_4x4x1_16b_f32 v[16:19], v34, v96, v[16:19]
	v_mfma_f32_4x4x1_16b_f32 v[4:7], v46, v89, v[4:7]
	v_mfma_f32_4x4x1_16b_f32 v[8:11], v46, v97, v[8:11]
	v_mfma_f32_4x4x1_16b_f32 v[12:15], v50, v89, v[12:15]
	v_mfma_f32_4x4x1_16b_f32 v[16:19], v50, v97, v[16:19]
	v_mfma_f32_4x4x1_16b_f32 v[4:7], v31, v90, v[4:7]
	v_mfma_f32_4x4x1_16b_f32 v[8:11], v31, v98, v[8:11]
	v_mfma_f32_4x4x1_16b_f32 v[12:15], v35, v90, v[12:15]
	v_mfma_f32_4x4x1_16b_f32 v[16:19], v35, v98, v[16:19]
	v_mfma_f32_4x4x1_16b_f32 v[4:7], v47, v91, v[4:7]
	v_mfma_f32_4x4x1_16b_f32 v[8:11], v47, v99, v[8:11]
	v_mfma_f32_4x4x1_16b_f32 v[12:15], v51, v91, v[12:15]
	v_mfma_f32_4x4x1_16b_f32 v[16:19], v51, v99, v[16:19]
	s_add_i32 s36, s13, 2
	s_and_b32 s36, s36, 7
	s_lshl_b32 s1, s36, 13
	v_add_u32_e32 v118, s1, v117
	ds_read_b128 v[68:71], v118 offset:0
	ds_read_b128 v[72:75], v118 offset:1024
	ds_read_b128 v[76:79], v118 offset:2048
	ds_read_b128 v[80:83], v118 offset:3072
	s_waitcnt vmcnt(8)
	ds_write_b128 v3, v[100:103] offset:0
	ds_write_b128 v3, v[104:107] offset:1152
	ds_write_b128 v3, v[108:111] offset:2304
	ds_write_b128 v3, v[112:115] offset:3456
	s_add_i32 s36, s13, 5
	s_and_b32 s36, s36, 7
	s_lshl_b32 s1, s36, 9
	s_add_u32 s10, s6, s1
	s_addc_u32 s11, s7, 0
	global_load_dwordx4 v[100:103], v2, s[10:11]
	s_add_u32 s10, s10, 0x2000
	s_addc_u32 s11, s11, 0
	global_load_dwordx4 v[104:107], v2, s[10:11]
	s_add_u32 s10, s10, 0x2000
	s_addc_u32 s11, s11, 0
	global_load_dwordx4 v[108:111], v2, s[10:11]
	s_add_u32 s10, s10, 0x2000
	s_addc_u32 s11, s11, 0
	global_load_dwordx4 v[112:115], v2, s[10:11]
	s_add_i32 s36, s13, 2
	s_and_b32 s36, s36, 7
	s_waitcnt lgkmcnt(0)
	ds_read_b128 v[36:39], v116 offset:0
	ds_read_b128 v[40:43], v116 offset:2304
	ds_read_b128 v[44:47], v116 offset:256
	ds_read_b128 v[48:51], v116 offset:2560
	s_lshl_b32 s1, s36, 13
	s_add_u32 s1, s1, 0x1000
	v_add_u32_e32 v118, s1, v117
	ds_read_b128 v[84:87], v118 offset:0
	ds_read_b128 v[88:91], v118 offset:1024
	ds_read_b128 v[92:95], v118 offset:2048
	ds_read_b128 v[96:99], v118 offset:3072
	s_waitcnt lgkmcnt(6)
	v_lshlrev_b32_e32 v20, 16, v36
	v_and_b32_e32 v36, 0xffff0000, v36
	v_lshlrev_b32_e32 v21, 16, v37
	v_and_b32_e32 v37, 0xffff0000, v37
	v_lshlrev_b32_e32 v22, 16, v38
	v_and_b32_e32 v38, 0xffff0000, v38
	v_lshlrev_b32_e32 v23, 16, v39
	v_and_b32_e32 v39, 0xffff0000, v39
	v_lshlrev_b32_e32 v24, 16, v40
	v_and_b32_e32 v40, 0xffff0000, v40
	v_lshlrev_b32_e32 v25, 16, v41
	v_and_b32_e32 v41, 0xffff0000, v41
	v_lshlrev_b32_e32 v26, 16, v42
	v_and_b32_e32 v42, 0xffff0000, v42
	v_lshlrev_b32_e32 v27, 16, v43
	v_and_b32_e32 v43, 0xffff0000, v43
	v_mfma_f32_4x4x1_16b_f32 v[4:7], v20, v68, v[4:7]
	v_mfma_f32_4x4x1_16b_f32 v[8:11], v20, v76, v[8:11]
	s_waitcnt lgkmcnt(4)
	v_mfma_f32_4x4x1_16b_f32 v[12:15], v24, v68, v[12:15]
	v_lshlrev_b32_e32 v28, 16, v44
	v_mfma_f32_4x4x1_16b_f32 v[16:19], v24, v76, v[16:19]
	v_mfma_f32_4x4x1_16b_f32 v[4:7], v36, v69, v[4:7]
	v_and_b32_e32 v44, 0xffff0000, v44
	v_mfma_f32_4x4x1_16b_f32 v[8:11], v36, v77, v[8:11]
	v_mfma_f32_4x4x1_16b_f32 v[12:15], v40, v69, v[12:15]
	v_lshlrev_b32_e32 v29, 16, v45
	v_mfma_f32_4x4x1_16b_f32 v[16:19], v40, v77, v[16:19]
	v_mfma_f32_4x4x1_16b_f32 v[4:7], v21, v70, v[4:7]
	v_and_b32_e32 v45, 0xffff0000, v45
	v_mfma_f32_4x4x1_16b_f32 v[8:11], v21, v78, v[8:11]
	v_mfma_f32_4x4x1_16b_f32 v[12:15], v25, v70, v[12:15]
	v_lshlrev_b32_e32 v30, 16, v46
	v_mfma_f32_4x4x1_16b_f32 v[16:19], v25, v78, v[16:19]
	v_mfma_f32_4x4x1_16b_f32 v[4:7], v37, v71, v[4:7]
	v_and_b32_e32 v46, 0xffff0000, v46
	v_mfma_f32_4x4x1_16b_f32 v[8:11], v37, v79, v[8:11]
	v_mfma_f32_4x4x1_16b_f32 v[12:15], v41, v71, v[12:15]
	v_lshlrev_b32_e32 v31, 16, v47
	v_mfma_f32_4x4x1_16b_f32 v[16:19], v41, v79, v[16:19]
	v_mfma_f32_4x4x1_16b_f32 v[4:7], v22, v72, v[4:7]
	v_and_b32_e32 v47, 0xffff0000, v47
	v_mfma_f32_4x4x1_16b_f32 v[8:11], v22, v80, v[8:11]
	v_mfma_f32_4x4x1_16b_f32 v[12:15], v26, v72, v[12:15]
	v_lshlrev_b32_e32 v32, 16, v48
	v_mfma_f32_4x4x1_16b_f32 v[16:19], v26, v80, v[16:19]
	v_mfma_f32_4x4x1_16b_f32 v[4:7], v38, v73, v[4:7]
	v_and_b32_e32 v48, 0xffff0000, v48
	v_mfma_f32_4x4x1_16b_f32 v[8:11], v38, v81, v[8:11]
	v_mfma_f32_4x4x1_16b_f32 v[12:15], v42, v73, v[12:15]
	v_lshlrev_b32_e32 v33, 16, v49
	v_mfma_f32_4x4x1_16b_f32 v[16:19], v42, v81, v[16:19]
	v_mfma_f32_4x4x1_16b_f32 v[4:7], v23, v74, v[4:7]
	v_and_b32_e32 v49, 0xffff0000, v49
	v_mfma_f32_4x4x1_16b_f32 v[8:11], v23, v82, v[8:11]
	v_mfma_f32_4x4x1_16b_f32 v[12:15], v27, v74, v[12:15]
	v_lshlrev_b32_e32 v34, 16, v50
	v_mfma_f32_4x4x1_16b_f32 v[16:19], v27, v82, v[16:19]
	v_mfma_f32_4x4x1_16b_f32 v[4:7], v39, v75, v[4:7]
	v_and_b32_e32 v50, 0xffff0000, v50
	v_mfma_f32_4x4x1_16b_f32 v[8:11], v39, v83, v[8:11]
	v_mfma_f32_4x4x1_16b_f32 v[12:15], v43, v75, v[12:15]
	v_lshlrev_b32_e32 v35, 16, v51
	v_mfma_f32_4x4x1_16b_f32 v[16:19], v43, v83, v[16:19]
	s_waitcnt lgkmcnt(0)
; __global__ void __launch_bounds__(NWAVES * 64, 2) fwd_megakernel(Args args) {
;     ...
;                     for (int jj = 0; jj < 4; ++jj) pw[q][jj] = *(const u32x4*)(XB + (size_t)(m0 + q) * DM + 512 * jj + 8 * ln); }
; #pragma unroll
;                 for (int q = 0; q < 4; ++q) { float d = 0.f;
; #pragma unroll
;                     for (int jj = 0; jj < 4; ++jj) { const u32x4 w = pw[q][jj];
;                         d += __uint_as_float(w.x << 16) * wreg[8 * jj + 0] + __uint_as_float(w.x & 0xffff0000u) * wreg[8 * jj + 1] + __uint_as_float(w.y << 16) * wreg[8 * jj + 2] + __uint_as_float(w.y & 0xffff0000u) * wreg[8 * jj + 3]
;                            + __uint_as_float(w.z << 16) * wreg[8 * jj + 4] + __uint_as_float(w.z & 0xffff0000u) * wreg[8 * jj + 5] + __uint_as_float(w.w << 16) * wreg[8 * jj + 6] + __uint_as_float(w.w & 0xffff0000u) * wreg[8 * jj + 7]; }
	v_mfma_f32_4x4x1_16b_f32 v[4:7], v28, v84, v[4:7]
	v_mfma_f32_4x4x1_16b_f32 v[8:11], v28, v92, v[8:11]
	v_mfma_f32_4x4x1_16b_f32 v[12:15], v32, v84, v[12:15]
	v_mfma_f32_4x4x1_16b_f32 v[16:19], v32, v92, v[16:19]
	v_mfma_f32_4x4x1_16b_f32 v[4:7], v44, v85, v[4:7]
	v_mfma_f32_4x4x1_16b_f32 v[8:11], v44, v93, v[8:11]
	v_mfma_f32_4x4x1_16b_f32 v[12:15], v48, v85, v[12:15]
	v_mfma_f32_4x4x1_16b_f32 v[16:19], v48, v93, v[16:19]
	v_mfma_f32_4x4x1_16b_f32 v[4:7], v29, v86, v[4:7]
	v_mfma_f32_4x4x1_16b_f32 v[8:11], v29, v94, v[8:11]
	v_mfma_f32_4x4x1_16b_f32 v[12:15], v33, v86, v[12:15]
	v_mfma_f32_4x4x1_16b_f32 v[16:19], v33, v94, v[16:19]
	v_mfma_f32_4x4x1_16b_f32 v[4:7], v45, v87, v[4:7]
	v_mfma_f32_4x4x1_16b_f32 v[8:11], v45, v95, v[8:11]
	v_mfma_f32_4x4x1_16b_f32 v[12:15], v49, v87, v[12:15]
	v_mfma_f32_4x4x1_16b_f32 v[16:19], v49, v95, v[16:19]
	v_mfma_f32_4x4x1_16b_f32 v[4:7], v30, v88, v[4:7]
	v_mfma_f32_4x4x1_16b_f32 v[8:11], v30, v96, v[8:11]
	v_mfma_f32_4x4x1_16b_f32 v[12:15], v34, v88, v[12:15]
	v_mfma_f32_4x4x1_16b_f32 v[16:19], v34, v96, v[16:19]
	v_mfma_f32_4x4x1_16b_f32 v[4:7], v46, v89, v[4:7]
	v_mfma_f32_4x4x1_16b_f32 v[8:11], v46, v97, v[8:11]
	v_mfma_f32_4x4x1_16b_f32 v[12:15], v50, v89, v[12:15]
	v_mfma_f32_4x4x1_16b_f32 v[16:19], v50, v97, v[16:19]
	v_mfma_f32_4x4x1_16b_f32 v[4:7], v31, v90, v[4:7]
	v_mfma_f32_4x4x1_16b_f32 v[8:11], v31, v98, v[8:11]
	v_mfma_f32_4x4x1_16b_f32 v[12:15], v35, v90, v[12:15]
	v_mfma_f32_4x4x1_16b_f32 v[16:19], v35, v98, v[16:19]
	v_mfma_f32_4x4x1_16b_f32 v[4:7], v47, v91, v[4:7]
	v_mfma_f32_4x4x1_16b_f32 v[8:11], v47, v99, v[8:11]
	v_mfma_f32_4x4x1_16b_f32 v[12:15], v51, v91, v[12:15]
	v_mfma_f32_4x4x1_16b_f32 v[16:19], v51, v99, v[16:19]
	s_add_i32 s36, s13, 3
	s_and_b32 s36, s36, 7
	s_lshl_b32 s1, s36, 13
	v_add_u32_e32 v118, s1, v117
	ds_read_b128 v[68:71], v118 offset:0
	ds_read_b128 v[72:75], v118 offset:1024
	ds_read_b128 v[76:79], v118 offset:2048
	ds_read_b128 v[80:83], v118 offset:3072
	s_waitcnt vmcnt(8)
	ds_write_b128 v3, v[120:123] offset:0
	ds_write_b128 v3, v[124:127] offset:1152
	ds_write_b128 v3, v[128:131] offset:2304
	ds_write_b128 v3, v[132:135] offset:3456
	s_add_i32 s36, s13, 6
	s_and_b32 s36, s36, 7
	s_lshl_b32 s1, s36, 9
	s_add_u32 s10, s6, s1
	s_addc_u32 s11, s7, 0
	global_load_dwordx4 v[120:123], v2, s[10:11]
	s_add_u32 s10, s10, 0x2000
	s_addc_u32 s11, s11, 0
	global_load_dwordx4 v[124:127], v2, s[10:11]
	s_add_u32 s10, s10, 0x2000
	s_addc_u32 s11, s11, 0
	global_load_dwordx4 v[128:131], v2, s[10:11]
	s_add_u32 s10, s10, 0x2000
	s_addc_u32 s11, s11, 0
	global_load_dwordx4 v[132:135], v2, s[10:11]
	s_add_i32 s36, s13, 3
	s_and_b32 s36, s36, 7
	s_waitcnt lgkmcnt(0)
	ds_read_b128 v[36:39], v116 offset:0
	ds_read_b128 v[40:43], v116 offset:2304
	ds_read_b128 v[44:47], v116 offset:256
	ds_read_b128 v[48:51], v116 offset:2560
	s_lshl_b32 s1, s36, 13
	s_add_u32 s1, s1, 0x1000
	v_add_u32_e32 v118, s1, v117
	ds_read_b128 v[84:87], v118 offset:0
	ds_read_b128 v[88:91], v118 offset:1024
	ds_read_b128 v[92:95], v118 offset:2048
	ds_read_b128 v[96:99], v118 offset:3072
	s_waitcnt lgkmcnt(6)
	v_lshlrev_b32_e32 v20, 16, v36
	v_and_b32_e32 v36, 0xffff0000, v36
	v_lshlrev_b32_e32 v21, 16, v37
	v_and_b32_e32 v37, 0xffff0000, v37
	v_lshlrev_b32_e32 v22, 16, v38
	v_and_b32_e32 v38, 0xffff0000, v38
	v_lshlrev_b32_e32 v23, 16, v39
	v_and_b32_e32 v39, 0xffff0000, v39
	v_lshlrev_b32_e32 v24, 16, v40
	v_and_b32_e32 v40, 0xffff0000, v40
	v_lshlrev_b32_e32 v25, 16, v41
	v_and_b32_e32 v41, 0xffff0000, v41
	v_lshlrev_b32_e32 v26, 16, v42
	v_and_b32_e32 v42, 0xffff0000, v42
	v_lshlrev_b32_e32 v27, 16, v43
	v_and_b32_e32 v43, 0xffff0000, v43
	v_mfma_f32_4x4x1_16b_f32 v[4:7], v20, v68, v[4:7]
	v_mfma_f32_4x4x1_16b_f32 v[8:11], v20, v76, v[8:11]
	s_waitcnt lgkmcnt(4)
	v_mfma_f32_4x4x1_16b_f32 v[12:15], v24, v68, v[12:15]
	v_lshlrev_b32_e32 v28, 16, v44
	v_mfma_f32_4x4x1_16b_f32 v[16:19], v24, v76, v[16:19]
	v_mfma_f32_4x4x1_16b_f32 v[4:7], v36, v69, v[4:7]
	v_and_b32_e32 v44, 0xffff0000, v44
	v_mfma_f32_4x4x1_16b_f32 v[8:11], v36, v77, v[8:11]
	v_mfma_f32_4x4x1_16b_f32 v[12:15], v40, v69, v[12:15]
	v_lshlrev_b32_e32 v29, 16, v45
	v_mfma_f32_4x4x1_16b_f32 v[16:19], v40, v77, v[16:19]
	v_mfma_f32_4x4x1_16b_f32 v[4:7], v21, v70, v[4:7]
	v_and_b32_e32 v45, 0xffff0000, v45
	v_mfma_f32_4x4x1_16b_f32 v[8:11], v21, v78, v[8:11]
	v_mfma_f32_4x4x1_16b_f32 v[12:15], v25, v70, v[12:15]
	v_lshlrev_b32_e32 v30, 16, v46
	v_mfma_f32_4x4x1_16b_f32 v[16:19], v25, v78, v[16:19]
	v_mfma_f32_4x4x1_16b_f32 v[4:7], v37, v71, v[4:7]
	v_and_b32_e32 v46, 0xffff0000, v46
	v_mfma_f32_4x4x1_16b_f32 v[8:11], v37, v79, v[8:11]
	v_mfma_f32_4x4x1_16b_f32 v[12:15], v41, v71, v[12:15]
	v_lshlrev_b32_e32 v31, 16, v47
	v_mfma_f32_4x4x1_16b_f32 v[16:19], v41, v79, v[16:19]
	v_mfma_f32_4x4x1_16b_f32 v[4:7], v22, v72, v[4:7]
	v_and_b32_e32 v47, 0xffff0000, v47
	v_mfma_f32_4x4x1_16b_f32 v[8:11], v22, v80, v[8:11]
	v_mfma_f32_4x4x1_16b_f32 v[12:15], v26, v72, v[12:15]
	v_lshlrev_b32_e32 v32, 16, v48
	v_mfma_f32_4x4x1_16b_f32 v[16:19], v26, v80, v[16:19]
	v_mfma_f32_4x4x1_16b_f32 v[4:7], v38, v73, v[4:7]
	v_and_b32_e32 v48, 0xffff0000, v48
	v_mfma_f32_4x4x1_16b_f32 v[8:11], v38, v81, v[8:11]
	v_mfma_f32_4x4x1_16b_f32 v[12:15], v42, v73, v[12:15]
	v_lshlrev_b32_e32 v33, 16, v49
	v_mfma_f32_4x4x1_16b_f32 v[16:19], v42, v81, v[16:19]
	v_mfma_f32_4x4x1_16b_f32 v[4:7], v23, v74, v[4:7]
	v_and_b32_e32 v49, 0xffff0000, v49
	v_mfma_f32_4x4x1_16b_f32 v[8:11], v23, v82, v[8:11]
	v_mfma_f32_4x4x1_16b_f32 v[12:15], v27, v74, v[12:15]
	v_lshlrev_b32_e32 v34, 16, v50
	v_mfma_f32_4x4x1_16b_f32 v[16:19], v27, v82, v[16:19]
	v_mfma_f32_4x4x1_16b_f32 v[4:7], v39, v75, v[4:7]
	v_and_b32_e32 v50, 0xffff0000, v50
	v_mfma_f32_4x4x1_16b_f32 v[8:11], v39, v83, v[8:11]
	v_mfma_f32_4x4x1_16b_f32 v[12:15], v43, v75, v[12:15]
	v_lshlrev_b32_e32 v35, 16, v51
	v_mfma_f32_4x4x1_16b_f32 v[16:19], v43, v83, v[16:19]
	s_waitcnt lgkmcnt(0)
; __global__ void __launch_bounds__(NWAVES * 64, 2) fwd_megakernel(Args args) {
;     ...
;                     for (int jj = 0; jj < 4; ++jj) pw[q][jj] = *(const u32x4*)(XB + (size_t)(m0 + q) * DM + 512 * jj + 8 * ln); }
; #pragma unroll
;                 for (int q = 0; q < 4; ++q) { float d = 0.f;
; #pragma unroll
;                     for (int jj = 0; jj < 4; ++jj) { const u32x4 w = pw[q][jj];
;                         d += __uint_as_float(w.x << 16) * wreg[8 * jj + 0] + __uint_as_float(w.x & 0xffff0000u) * wreg[8 * jj + 1] + __uint_as_float(w.y << 16) * wreg[8 * jj + 2] + __uint_as_float(w.y & 0xffff0000u) * wreg[8 * jj + 3]
;                            + __uint_as_float(w.z << 16) * wreg[8 * jj + 4] + __uint_as_float(w.z & 0xffff0000u) * wreg[8 * jj + 5] + __uint_as_float(w.w << 16) * wreg[8 * jj + 6] + __uint_as_float(w.w & 0xffff0000u) * wreg[8 * jj + 7]; }
	v_mfma_f32_4x4x1_16b_f32 v[4:7], v28, v84, v[4:7]
	v_mfma_f32_4x4x1_16b_f32 v[8:11], v28, v92, v[8:11]
	v_mfma_f32_4x4x1_16b_f32 v[12:15], v32, v84, v[12:15]
	v_mfma_f32_4x4x1_16b_f32 v[16:19], v32, v92, v[16:19]
	v_mfma_f32_4x4x1_16b_f32 v[4:7], v44, v85, v[4:7]
	v_mfma_f32_4x4x1_16b_f32 v[8:11], v44, v93, v[8:11]
	v_mfma_f32_4x4x1_16b_f32 v[12:15], v48, v85, v[12:15]
	v_mfma_f32_4x4x1_16b_f32 v[16:19], v48, v93, v[16:19]
	v_mfma_f32_4x4x1_16b_f32 v[4:7], v29, v86, v[4:7]
	v_mfma_f32_4x4x1_16b_f32 v[8:11], v29, v94, v[8:11]
	v_mfma_f32_4x4x1_16b_f32 v[12:15], v33, v86, v[12:15]
	v_mfma_f32_4x4x1_16b_f32 v[16:19], v33, v94, v[16:19]
	v_mfma_f32_4x4x1_16b_f32 v[4:7], v45, v87, v[4:7]
	v_mfma_f32_4x4x1_16b_f32 v[8:11], v45, v95, v[8:11]
	v_mfma_f32_4x4x1_16b_f32 v[12:15], v49, v87, v[12:15]
	v_mfma_f32_4x4x1_16b_f32 v[16:19], v49, v95, v[16:19]
	v_mfma_f32_4x4x1_16b_f32 v[4:7], v30, v88, v[4:7]
	v_mfma_f32_4x4x1_16b_f32 v[8:11], v30, v96, v[8:11]
	v_mfma_f32_4x4x1_16b_f32 v[12:15], v34, v88, v[12:15]
	v_mfma_f32_4x4x1_16b_f32 v[16:19], v34, v96, v[16:19]
	v_mfma_f32_4x4x1_16b_f32 v[4:7], v46, v89, v[4:7]
	v_mfma_f32_4x4x1_16b_f32 v[8:11], v46, v97, v[8:11]
	v_mfma_f32_4x4x1_16b_f32 v[12:15], v50, v89, v[12:15]
	v_mfma_f32_4x4x1_16b_f32 v[16:19], v50, v97, v[16:19]
	v_mfma_f32_4x4x1_16b_f32 v[4:7], v31, v90, v[4:7]
	v_mfma_f32_4x4x1_16b_f32 v[8:11], v31, v98, v[8:11]
	v_mfma_f32_4x4x1_16b_f32 v[12:15], v35, v90, v[12:15]
	v_mfma_f32_4x4x1_16b_f32 v[16:19], v35, v98, v[16:19]
	v_mfma_f32_4x4x1_16b_f32 v[4:7], v47, v91, v[4:7]
	v_mfma_f32_4x4x1_16b_f32 v[8:11], v47, v99, v[8:11]
	v_mfma_f32_4x4x1_16b_f32 v[12:15], v51, v91, v[12:15]
	v_mfma_f32_4x4x1_16b_f32 v[16:19], v51, v99, v[16:19]
	s_add_i32 s36, s13, 4
	s_and_b32 s36, s36, 7
	s_lshl_b32 s1, s36, 13
	v_add_u32_e32 v118, s1, v117
	ds_read_b128 v[68:71], v118 offset:0
	ds_read_b128 v[72:75], v118 offset:1024
	ds_read_b128 v[76:79], v118 offset:2048
	ds_read_b128 v[80:83], v118 offset:3072
	s_waitcnt vmcnt(8)
	ds_write_b128 v3, v[136:139] offset:0
	ds_write_b128 v3, v[140:143] offset:1152
	ds_write_b128 v3, v[144:147] offset:2304
	ds_write_b128 v3, v[148:151] offset:3456
	s_add_i32 s36, s13, 7
	s_and_b32 s36, s36, 7
	s_lshl_b32 s1, s36, 9
	s_add_u32 s10, s6, s1
	s_addc_u32 s11, s7, 0
	global_load_dwordx4 v[136:139], v2, s[10:11]
	s_add_u32 s10, s10, 0x2000
	s_addc_u32 s11, s11, 0
	global_load_dwordx4 v[140:143], v2, s[10:11]
	s_add_u32 s10, s10, 0x2000
	s_addc_u32 s11, s11, 0
	global_load_dwordx4 v[144:147], v2, s[10:11]
	s_add_u32 s10, s10, 0x2000
	s_addc_u32 s11, s11, 0
	global_load_dwordx4 v[148:151], v2, s[10:11]
	s_add_i32 s36, s13, 4
	s_and_b32 s36, s36, 7
	s_waitcnt lgkmcnt(0)
	ds_read_b128 v[36:39], v116 offset:0
	ds_read_b128 v[40:43], v116 offset:2304
	ds_read_b128 v[44:47], v116 offset:256
	ds_read_b128 v[48:51], v116 offset:2560
	s_lshl_b32 s1, s36, 13
	s_add_u32 s1, s1, 0x1000
	v_add_u32_e32 v118, s1, v117
	ds_read_b128 v[84:87], v118 offset:0
	ds_read_b128 v[88:91], v118 offset:1024
	ds_read_b128 v[92:95], v118 offset:2048
	ds_read_b128 v[96:99], v118 offset:3072
	s_waitcnt lgkmcnt(6)
	v_lshlrev_b32_e32 v20, 16, v36
	v_and_b32_e32 v36, 0xffff0000, v36
	v_lshlrev_b32_e32 v21, 16, v37
	v_and_b32_e32 v37, 0xffff0000, v37
	v_lshlrev_b32_e32 v22, 16, v38
	v_and_b32_e32 v38, 0xffff0000, v38
	v_lshlrev_b32_e32 v23, 16, v39
	v_and_b32_e32 v39, 0xffff0000, v39
	v_lshlrev_b32_e32 v24, 16, v40
	v_and_b32_e32 v40, 0xffff0000, v40
	v_lshlrev_b32_e32 v25, 16, v41
	v_and_b32_e32 v41, 0xffff0000, v41
	v_lshlrev_b32_e32 v26, 16, v42
	v_and_b32_e32 v42, 0xffff0000, v42
	v_lshlrev_b32_e32 v27, 16, v43
	v_and_b32_e32 v43, 0xffff0000, v43
	v_mfma_f32_4x4x1_16b_f32 v[4:7], v20, v68, v[4:7]
	v_mfma_f32_4x4x1_16b_f32 v[8:11], v20, v76, v[8:11]
	s_waitcnt lgkmcnt(4)
	v_mfma_f32_4x4x1_16b_f32 v[12:15], v24, v68, v[12:15]
	v_lshlrev_b32_e32 v28, 16, v44
	v_mfma_f32_4x4x1_16b_f32 v[16:19], v24, v76, v[16:19]
	v_mfma_f32_4x4x1_16b_f32 v[4:7], v36, v69, v[4:7]
	v_and_b32_e32 v44, 0xffff0000, v44
	v_mfma_f32_4x4x1_16b_f32 v[8:11], v36, v77, v[8:11]
	v_mfma_f32_4x4x1_16b_f32 v[12:15], v40, v69, v[12:15]
	v_lshlrev_b32_e32 v29, 16, v45
	v_mfma_f32_4x4x1_16b_f32 v[16:19], v40, v77, v[16:19]
	v_mfma_f32_4x4x1_16b_f32 v[4:7], v21, v70, v[4:7]
	v_and_b32_e32 v45, 0xffff0000, v45
	v_mfma_f32_4x4x1_16b_f32 v[8:11], v21, v78, v[8:11]
	v_mfma_f32_4x4x1_16b_f32 v[12:15], v25, v70, v[12:15]
	v_lshlrev_b32_e32 v30, 16, v46
	v_mfma_f32_4x4x1_16b_f32 v[16:19], v25, v78, v[16:19]
	v_mfma_f32_4x4x1_16b_f32 v[4:7], v37, v71, v[4:7]
	v_and_b32_e32 v46, 0xffff0000, v46
	v_mfma_f32_4x4x1_16b_f32 v[8:11], v37, v79, v[8:11]
	v_mfma_f32_4x4x1_16b_f32 v[12:15], v41, v71, v[12:15]
	v_lshlrev_b32_e32 v31, 16, v47
	v_mfma_f32_4x4x1_16b_f32 v[16:19], v41, v79, v[16:19]
	v_mfma_f32_4x4x1_16b_f32 v[4:7], v22, v72, v[4:7]
	v_and_b32_e32 v47, 0xffff0000, v47
	v_mfma_f32_4x4x1_16b_f32 v[8:11], v22, v80, v[8:11]
	v_mfma_f32_4x4x1_16b_f32 v[12:15], v26, v72, v[12:15]
	v_lshlrev_b32_e32 v32, 16, v48
	v_mfma_f32_4x4x1_16b_f32 v[16:19], v26, v80, v[16:19]
	v_mfma_f32_4x4x1_16b_f32 v[4:7], v38, v73, v[4:7]
	v_and_b32_e32 v48, 0xffff0000, v48
	v_mfma_f32_4x4x1_16b_f32 v[8:11], v38, v81, v[8:11]
	v_mfma_f32_4x4x1_16b_f32 v[12:15], v42, v73, v[12:15]
	v_lshlrev_b32_e32 v33, 16, v49
	v_mfma_f32_4x4x1_16b_f32 v[16:19], v42, v81, v[16:19]
	v_mfma_f32_4x4x1_16b_f32 v[4:7], v23, v74, v[4:7]
	v_and_b32_e32 v49, 0xffff0000, v49
	v_mfma_f32_4x4x1_16b_f32 v[8:11], v23, v82, v[8:11]
	v_mfma_f32_4x4x1_16b_f32 v[12:15], v27, v74, v[12:15]
	v_lshlrev_b32_e32 v34, 16, v50
	v_mfma_f32_4x4x1_16b_f32 v[16:19], v27, v82, v[16:19]
	v_mfma_f32_4x4x1_16b_f32 v[4:7], v39, v75, v[4:7]
	v_and_b32_e32 v50, 0xffff0000, v50
	v_mfma_f32_4x4x1_16b_f32 v[8:11], v39, v83, v[8:11]
	v_mfma_f32_4x4x1_16b_f32 v[12:15], v43, v75, v[12:15]
	v_lshlrev_b32_e32 v35, 16, v51
	v_mfma_f32_4x4x1_16b_f32 v[16:19], v43, v83, v[16:19]
	s_waitcnt lgkmcnt(0)
; __global__ void __launch_bounds__(NWAVES * 64, 2) fwd_megakernel(Args args) {
;     ...
;                     for (int jj = 0; jj < 4; ++jj) pw[q][jj] = *(const u32x4*)(XB + (size_t)(m0 + q) * DM + 512 * jj + 8 * ln); }
; #pragma unroll
;                 for (int q = 0; q < 4; ++q) { float d = 0.f;
; #pragma unroll
;                     for (int jj = 0; jj < 4; ++jj) { const u32x4 w = pw[q][jj];
;                         d += __uint_as_float(w.x << 16) * wreg[8 * jj + 0] + __uint_as_float(w.x & 0xffff0000u) * wreg[8 * jj + 1] + __uint_as_float(w.y << 16) * wreg[8 * jj + 2] + __uint_as_float(w.y & 0xffff0000u) * wreg[8 * jj + 3]
;                            + __uint_as_float(w.z << 16) * wreg[8 * jj + 4] + __uint_as_float(w.z & 0xffff0000u) * wreg[8 * jj + 5] + __uint_as_float(w.w << 16) * wreg[8 * jj + 6] + __uint_as_float(w.w & 0xffff0000u) * wreg[8 * jj + 7]; }
	v_mfma_f32_4x4x1_16b_f32 v[4:7], v28, v84, v[4:7]
	v_mfma_f32_4x4x1_16b_f32 v[8:11], v28, v92, v[8:11]
	v_mfma_f32_4x4x1_16b_f32 v[12:15], v32, v84, v[12:15]
	v_mfma_f32_4x4x1_16b_f32 v[16:19], v32, v92, v[16:19]
	v_mfma_f32_4x4x1_16b_f32 v[4:7], v44, v85, v[4:7]
	v_mfma_f32_4x4x1_16b_f32 v[8:11], v44, v93, v[8:11]
	v_mfma_f32_4x4x1_16b_f32 v[12:15], v48, v85, v[12:15]
	v_mfma_f32_4x4x1_16b_f32 v[16:19], v48, v93, v[16:19]
	v_mfma_f32_4x4x1_16b_f32 v[4:7], v29, v86, v[4:7]
	v_mfma_f32_4x4x1_16b_f32 v[8:11], v29, v94, v[8:11]
	v_mfma_f32_4x4x1_16b_f32 v[12:15], v33, v86, v[12:15]
	v_mfma_f32_4x4x1_16b_f32 v[16:19], v33, v94, v[16:19]
	v_mfma_f32_4x4x1_16b_f32 v[4:7], v45, v87, v[4:7]
	v_mfma_f32_4x4x1_16b_f32 v[8:11], v45, v95, v[8:11]
	v_mfma_f32_4x4x1_16b_f32 v[12:15], v49, v87, v[12:15]
	v_mfma_f32_4x4x1_16b_f32 v[16:19], v49, v95, v[16:19]
	v_mfma_f32_4x4x1_16b_f32 v[4:7], v30, v88, v[4:7]
	v_mfma_f32_4x4x1_16b_f32 v[8:11], v30, v96, v[8:11]
	v_mfma_f32_4x4x1_16b_f32 v[12:15], v34, v88, v[12:15]
	v_mfma_f32_4x4x1_16b_f32 v[16:19], v34, v96, v[16:19]
	v_mfma_f32_4x4x1_16b_f32 v[4:7], v46, v89, v[4:7]
	v_mfma_f32_4x4x1_16b_f32 v[8:11], v46, v97, v[8:11]
	v_mfma_f32_4x4x1_16b_f32 v[12:15], v50, v89, v[12:15]
	v_mfma_f32_4x4x1_16b_f32 v[16:19], v50, v97, v[16:19]
	v_mfma_f32_4x4x1_16b_f32 v[4:7], v31, v90, v[4:7]
	v_mfma_f32_4x4x1_16b_f32 v[8:11], v31, v98, v[8:11]
	v_mfma_f32_4x4x1_16b_f32 v[12:15], v35, v90, v[12:15]
	v_mfma_f32_4x4x1_16b_f32 v[16:19], v35, v98, v[16:19]
	v_mfma_f32_4x4x1_16b_f32 v[4:7], v47, v91, v[4:7]
	v_mfma_f32_4x4x1_16b_f32 v[8:11], v47, v99, v[8:11]
	v_mfma_f32_4x4x1_16b_f32 v[12:15], v51, v91, v[12:15]
	v_mfma_f32_4x4x1_16b_f32 v[16:19], v51, v99, v[16:19]
	s_add_i32 s36, s13, 5
	s_and_b32 s36, s36, 7
	s_lshl_b32 s1, s36, 13
	v_add_u32_e32 v118, s1, v117
	ds_read_b128 v[68:71], v118 offset:0
	ds_read_b128 v[72:75], v118 offset:1024
	ds_read_b128 v[76:79], v118 offset:2048
	ds_read_b128 v[80:83], v118 offset:3072
	s_waitcnt vmcnt(8)
	ds_write_b128 v3, v[100:103] offset:0
	ds_write_b128 v3, v[104:107] offset:1152
	ds_write_b128 v3, v[108:111] offset:2304
	ds_write_b128 v3, v[112:115] offset:3456
	s_waitcnt lgkmcnt(0)
	ds_read_b128 v[36:39], v116 offset:0
	ds_read_b128 v[40:43], v116 offset:2304
	ds_read_b128 v[44:47], v116 offset:256
	ds_read_b128 v[48:51], v116 offset:2560
	s_lshl_b32 s1, s36, 13
	s_add_u32 s1, s1, 0x1000
	v_add_u32_e32 v118, s1, v117
	ds_read_b128 v[84:87], v118 offset:0
	ds_read_b128 v[88:91], v118 offset:1024
	ds_read_b128 v[92:95], v118 offset:2048
	ds_read_b128 v[96:99], v118 offset:3072
	s_waitcnt lgkmcnt(6)
	v_lshlrev_b32_e32 v20, 16, v36
	v_and_b32_e32 v36, 0xffff0000, v36
	v_lshlrev_b32_e32 v21, 16, v37
	v_and_b32_e32 v37, 0xffff0000, v37
	v_lshlrev_b32_e32 v22, 16, v38
	v_and_b32_e32 v38, 0xffff0000, v38
	v_lshlrev_b32_e32 v23, 16, v39
	v_and_b32_e32 v39, 0xffff0000, v39
	v_lshlrev_b32_e32 v24, 16, v40
	v_and_b32_e32 v40, 0xffff0000, v40
	v_lshlrev_b32_e32 v25, 16, v41
	v_and_b32_e32 v41, 0xffff0000, v41
	v_lshlrev_b32_e32 v26, 16, v42
	v_and_b32_e32 v42, 0xffff0000, v42
	v_lshlrev_b32_e32 v27, 16, v43
	v_and_b32_e32 v43, 0xffff0000, v43
	v_mfma_f32_4x4x1_16b_f32 v[4:7], v20, v68, v[4:7]
	v_mfma_f32_4x4x1_16b_f32 v[8:11], v20, v76, v[8:11]
	s_waitcnt lgkmcnt(4)
	v_mfma_f32_4x4x1_16b_f32 v[12:15], v24, v68, v[12:15]
	v_lshlrev_b32_e32 v28, 16, v44
	v_mfma_f32_4x4x1_16b_f32 v[16:19], v24, v76, v[16:19]
	v_mfma_f32_4x4x1_16b_f32 v[4:7], v36, v69, v[4:7]
	v_and_b32_e32 v44, 0xffff0000, v44
	v_mfma_f32_4x4x1_16b_f32 v[8:11], v36, v77, v[8:11]
	v_mfma_f32_4x4x1_16b_f32 v[12:15], v40, v69, v[12:15]
	v_lshlrev_b32_e32 v29, 16, v45
	v_mfma_f32_4x4x1_16b_f32 v[16:19], v40, v77, v[16:19]
	v_mfma_f32_4x4x1_16b_f32 v[4:7], v21, v70, v[4:7]
	v_and_b32_e32 v45, 0xffff0000, v45
	v_mfma_f32_4x4x1_16b_f32 v[8:11], v21, v78, v[8:11]
	v_mfma_f32_4x4x1_16b_f32 v[12:15], v25, v70, v[12:15]
	v_lshlrev_b32_e32 v30, 16, v46
	v_mfma_f32_4x4x1_16b_f32 v[16:19], v25, v78, v[16:19]
	v_mfma_f32_4x4x1_16b_f32 v[4:7], v37, v71, v[4:7]
	v_and_b32_e32 v46, 0xffff0000, v46
	v_mfma_f32_4x4x1_16b_f32 v[8:11], v37, v79, v[8:11]
	v_mfma_f32_4x4x1_16b_f32 v[12:15], v41, v71, v[12:15]
	v_lshlrev_b32_e32 v31, 16, v47
	v_mfma_f32_4x4x1_16b_f32 v[16:19], v41, v79, v[16:19]
	v_mfma_f32_4x4x1_16b_f32 v[4:7], v22, v72, v[4:7]
	v_and_b32_e32 v47, 0xffff0000, v47
	v_mfma_f32_4x4x1_16b_f32 v[8:11], v22, v80, v[8:11]
	v_mfma_f32_4x4x1_16b_f32 v[12:15], v26, v72, v[12:15]
	v_lshlrev_b32_e32 v32, 16, v48
	v_mfma_f32_4x4x1_16b_f32 v[16:19], v26, v80, v[16:19]
	v_mfma_f32_4x4x1_16b_f32 v[4:7], v38, v73, v[4:7]
	v_and_b32_e32 v48, 0xffff0000, v48
	v_mfma_f32_4x4x1_16b_f32 v[8:11], v38, v81, v[8:11]
	v_mfma_f32_4x4x1_16b_f32 v[12:15], v42, v73, v[12:15]
	v_lshlrev_b32_e32 v33, 16, v49
	v_mfma_f32_4x4x1_16b_f32 v[16:19], v42, v81, v[16:19]
	v_mfma_f32_4x4x1_16b_f32 v[4:7], v23, v74, v[4:7]
	v_and_b32_e32 v49, 0xffff0000, v49
	v_mfma_f32_4x4x1_16b_f32 v[8:11], v23, v82, v[8:11]
	v_mfma_f32_4x4x1_16b_f32 v[12:15], v27, v74, v[12:15]
	v_lshlrev_b32_e32 v34, 16, v50
	v_mfma_f32_4x4x1_16b_f32 v[16:19], v27, v82, v[16:19]
	v_mfma_f32_4x4x1_16b_f32 v[4:7], v39, v75, v[4:7]
	v_and_b32_e32 v50, 0xffff0000, v50
	v_mfma_f32_4x4x1_16b_f32 v[8:11], v39, v83, v[8:11]
	v_mfma_f32_4x4x1_16b_f32 v[12:15], v43, v75, v[12:15]
	v_lshlrev_b32_e32 v35, 16, v51
	v_mfma_f32_4x4x1_16b_f32 v[16:19], v43, v83, v[16:19]
	s_waitcnt lgkmcnt(0)
; __global__ void __launch_bounds__(NWAVES * 64, 2) fwd_megakernel(Args args) {
;     ...
;                     for (int jj = 0; jj < 4; ++jj) pw[q][jj] = *(const u32x4*)(XB + (size_t)(m0 + q) * DM + 512 * jj + 8 * ln); }
; #pragma unroll
;                 for (int q = 0; q < 4; ++q) { float d = 0.f;
; #pragma unroll
;                     for (int jj = 0; jj < 4; ++jj) { const u32x4 w = pw[q][jj];
;                         d += __uint_as_float(w.x << 16) * wreg[8 * jj + 0] + __uint_as_float(w.x & 0xffff0000u) * wreg[8 * jj + 1] + __uint_as_float(w.y << 16) * wreg[8 * jj + 2] + __uint_as_float(w.y & 0xffff0000u) * wreg[8 * jj + 3]
;                            + __uint_as_float(w.z << 16) * wreg[8 * jj + 4] + __uint_as_float(w.z & 0xffff0000u) * wreg[8 * jj + 5] + __uint_as_float(w.w << 16) * wreg[8 * jj + 6] + __uint_as_float(w.w & 0xffff0000u) * wreg[8 * jj + 7]; }
	v_mfma_f32_4x4x1_16b_f32 v[4:7], v28, v84, v[4:7]
	v_mfma_f32_4x4x1_16b_f32 v[8:11], v28, v92, v[8:11]
	v_mfma_f32_4x4x1_16b_f32 v[12:15], v32, v84, v[12:15]
	v_mfma_f32_4x4x1_16b_f32 v[16:19], v32, v92, v[16:19]
	v_mfma_f32_4x4x1_16b_f32 v[4:7], v44, v85, v[4:7]
	v_mfma_f32_4x4x1_16b_f32 v[8:11], v44, v93, v[8:11]
	v_mfma_f32_4x4x1_16b_f32 v[12:15], v48, v85, v[12:15]
	v_mfma_f32_4x4x1_16b_f32 v[16:19], v48, v93, v[16:19]
	v_mfma_f32_4x4x1_16b_f32 v[4:7], v29, v86, v[4:7]
	v_mfma_f32_4x4x1_16b_f32 v[8:11], v29, v94, v[8:11]
	v_mfma_f32_4x4x1_16b_f32 v[12:15], v33, v86, v[12:15]
	v_mfma_f32_4x4x1_16b_f32 v[16:19], v33, v94, v[16:19]
	v_mfma_f32_4x4x1_16b_f32 v[4:7], v45, v87, v[4:7]
	v_mfma_f32_4x4x1_16b_f32 v[8:11], v45, v95, v[8:11]
	v_mfma_f32_4x4x1_16b_f32 v[12:15], v49, v87, v[12:15]
	v_mfma_f32_4x4x1_16b_f32 v[16:19], v49, v95, v[16:19]
	v_mfma_f32_4x4x1_16b_f32 v[4:7], v30, v88, v[4:7]
	v_mfma_f32_4x4x1_16b_f32 v[8:11], v30, v96, v[8:11]
	v_mfma_f32_4x4x1_16b_f32 v[12:15], v34, v88, v[12:15]
	v_mfma_f32_4x4x1_16b_f32 v[16:19], v34, v96, v[16:19]
	v_mfma_f32_4x4x1_16b_f32 v[4:7], v46, v89, v[4:7]
	v_mfma_f32_4x4x1_16b_f32 v[8:11], v46, v97, v[8:11]
	v_mfma_f32_4x4x1_16b_f32 v[12:15], v50, v89, v[12:15]
	v_mfma_f32_4x4x1_16b_f32 v[16:19], v50, v97, v[16:19]
	v_mfma_f32_4x4x1_16b_f32 v[4:7], v31, v90, v[4:7]
	v_mfma_f32_4x4x1_16b_f32 v[8:11], v31, v98, v[8:11]
	v_mfma_f32_4x4x1_16b_f32 v[12:15], v35, v90, v[12:15]
	v_mfma_f32_4x4x1_16b_f32 v[16:19], v35, v98, v[16:19]
	v_mfma_f32_4x4x1_16b_f32 v[4:7], v47, v91, v[4:7]
	v_mfma_f32_4x4x1_16b_f32 v[8:11], v47, v99, v[8:11]
	v_mfma_f32_4x4x1_16b_f32 v[12:15], v51, v91, v[12:15]
	v_mfma_f32_4x4x1_16b_f32 v[16:19], v51, v99, v[16:19]
	s_add_i32 s36, s13, 6
	s_and_b32 s36, s36, 7
	s_lshl_b32 s1, s36, 13
	v_add_u32_e32 v118, s1, v117
	ds_read_b128 v[68:71], v118 offset:0
	ds_read_b128 v[72:75], v118 offset:1024
	ds_read_b128 v[76:79], v118 offset:2048
	ds_read_b128 v[80:83], v118 offset:3072
	s_waitcnt vmcnt(4)
	ds_write_b128 v3, v[120:123] offset:0
	ds_write_b128 v3, v[124:127] offset:1152
	ds_write_b128 v3, v[128:131] offset:2304
	ds_write_b128 v3, v[132:135] offset:3456
	s_waitcnt lgkmcnt(0)
	ds_read_b128 v[36:39], v116 offset:0
	ds_read_b128 v[40:43], v116 offset:2304
	ds_read_b128 v[44:47], v116 offset:256
	ds_read_b128 v[48:51], v116 offset:2560
	s_lshl_b32 s1, s36, 13
	s_add_u32 s1, s1, 0x1000
	v_add_u32_e32 v118, s1, v117
	ds_read_b128 v[84:87], v118 offset:0
	ds_read_b128 v[88:91], v118 offset:1024
	ds_read_b128 v[92:95], v118 offset:2048
	ds_read_b128 v[96:99], v118 offset:3072
	s_waitcnt lgkmcnt(6)
	v_lshlrev_b32_e32 v20, 16, v36
	v_and_b32_e32 v36, 0xffff0000, v36
	v_lshlrev_b32_e32 v21, 16, v37
	v_and_b32_e32 v37, 0xffff0000, v37
	v_lshlrev_b32_e32 v22, 16, v38
	v_and_b32_e32 v38, 0xffff0000, v38
	v_lshlrev_b32_e32 v23, 16, v39
	v_and_b32_e32 v39, 0xffff0000, v39
	v_lshlrev_b32_e32 v24, 16, v40
	v_and_b32_e32 v40, 0xffff0000, v40
	v_lshlrev_b32_e32 v25, 16, v41
	v_and_b32_e32 v41, 0xffff0000, v41
	v_lshlrev_b32_e32 v26, 16, v42
	v_and_b32_e32 v42, 0xffff0000, v42
	v_lshlrev_b32_e32 v27, 16, v43
	v_and_b32_e32 v43, 0xffff0000, v43
	v_mfma_f32_4x4x1_16b_f32 v[4:7], v20, v68, v[4:7]
	v_mfma_f32_4x4x1_16b_f32 v[8:11], v20, v76, v[8:11]
	s_waitcnt lgkmcnt(4)
	v_mfma_f32_4x4x1_16b_f32 v[12:15], v24, v68, v[12:15]
	v_lshlrev_b32_e32 v28, 16, v44
	v_mfma_f32_4x4x1_16b_f32 v[16:19], v24, v76, v[16:19]
	v_mfma_f32_4x4x1_16b_f32 v[4:7], v36, v69, v[4:7]
	v_and_b32_e32 v44, 0xffff0000, v44
	v_mfma_f32_4x4x1_16b_f32 v[8:11], v36, v77, v[8:11]
	v_mfma_f32_4x4x1_16b_f32 v[12:15], v40, v69, v[12:15]
	v_lshlrev_b32_e32 v29, 16, v45
	v_mfma_f32_4x4x1_16b_f32 v[16:19], v40, v77, v[16:19]
	v_mfma_f32_4x4x1_16b_f32 v[4:7], v21, v70, v[4:7]
	v_and_b32_e32 v45, 0xffff0000, v45
	v_mfma_f32_4x4x1_16b_f32 v[8:11], v21, v78, v[8:11]
	v_mfma_f32_4x4x1_16b_f32 v[12:15], v25, v70, v[12:15]
	v_lshlrev_b32_e32 v30, 16, v46
	v_mfma_f32_4x4x1_16b_f32 v[16:19], v25, v78, v[16:19]
	v_mfma_f32_4x4x1_16b_f32 v[4:7], v37, v71, v[4:7]
	v_and_b32_e32 v46, 0xffff0000, v46
	v_mfma_f32_4x4x1_16b_f32 v[8:11], v37, v79, v[8:11]
	v_mfma_f32_4x4x1_16b_f32 v[12:15], v41, v71, v[12:15]
	v_lshlrev_b32_e32 v31, 16, v47
	v_mfma_f32_4x4x1_16b_f32 v[16:19], v41, v79, v[16:19]
	v_mfma_f32_4x4x1_16b_f32 v[4:7], v22, v72, v[4:7]
	v_and_b32_e32 v47, 0xffff0000, v47
	v_mfma_f32_4x4x1_16b_f32 v[8:11], v22, v80, v[8:11]
	v_mfma_f32_4x4x1_16b_f32 v[12:15], v26, v72, v[12:15]
	v_lshlrev_b32_e32 v32, 16, v48
	v_mfma_f32_4x4x1_16b_f32 v[16:19], v26, v80, v[16:19]
	v_mfma_f32_4x4x1_16b_f32 v[4:7], v38, v73, v[4:7]
	v_and_b32_e32 v48, 0xffff0000, v48
	v_mfma_f32_4x4x1_16b_f32 v[8:11], v38, v81, v[8:11]
	v_mfma_f32_4x4x1_16b_f32 v[12:15], v42, v73, v[12:15]
	v_lshlrev_b32_e32 v33, 16, v49
	v_mfma_f32_4x4x1_16b_f32 v[16:19], v42, v81, v[16:19]
	v_mfma_f32_4x4x1_16b_f32 v[4:7], v23, v74, v[4:7]
	v_and_b32_e32 v49, 0xffff0000, v49
	v_mfma_f32_4x4x1_16b_f32 v[8:11], v23, v82, v[8:11]
	v_mfma_f32_4x4x1_16b_f32 v[12:15], v27, v74, v[12:15]
	v_lshlrev_b32_e32 v34, 16, v50
	v_mfma_f32_4x4x1_16b_f32 v[16:19], v27, v82, v[16:19]
	v_mfma_f32_4x4x1_16b_f32 v[4:7], v39, v75, v[4:7]
	v_and_b32_e32 v50, 0xffff0000, v50
	v_mfma_f32_4x4x1_16b_f32 v[8:11], v39, v83, v[8:11]
	v_mfma_f32_4x4x1_16b_f32 v[12:15], v43, v75, v[12:15]
	v_lshlrev_b32_e32 v35, 16, v51
	v_mfma_f32_4x4x1_16b_f32 v[16:19], v43, v83, v[16:19]
	s_waitcnt lgkmcnt(0)
; __global__ void __launch_bounds__(NWAVES * 64, 2) fwd_megakernel(Args args) {
;     ...
;                     for (int jj = 0; jj < 4; ++jj) pw[q][jj] = *(const u32x4*)(XB + (size_t)(m0 + q) * DM + 512 * jj + 8 * ln); }
; #pragma unroll
;                 for (int q = 0; q < 4; ++q) { float d = 0.f;
; #pragma unroll
;                     for (int jj = 0; jj < 4; ++jj) { const u32x4 w = pw[q][jj];
;                         d += __uint_as_float(w.x << 16) * wreg[8 * jj + 0] + __uint_as_float(w.x & 0xffff0000u) * wreg[8 * jj + 1] + __uint_as_float(w.y << 16) * wreg[8 * jj + 2] + __uint_as_float(w.y & 0xffff0000u) * wreg[8 * jj + 3]
;                            + __uint_as_float(w.z << 16) * wreg[8 * jj + 4] + __uint_as_float(w.z & 0xffff0000u) * wreg[8 * jj + 5] + __uint_as_float(w.w << 16) * wreg[8 * jj + 6] + __uint_as_float(w.w & 0xffff0000u) * wreg[8 * jj + 7]; }
	v_mfma_f32_4x4x1_16b_f32 v[4:7], v28, v84, v[4:7]
	v_mfma_f32_4x4x1_16b_f32 v[8:11], v28, v92, v[8:11]
	v_mfma_f32_4x4x1_16b_f32 v[12:15], v32, v84, v[12:15]
	v_mfma_f32_4x4x1_16b_f32 v[16:19], v32, v92, v[16:19]
	v_mfma_f32_4x4x1_16b_f32 v[4:7], v44, v85, v[4:7]
	v_mfma_f32_4x4x1_16b_f32 v[8:11], v44, v93, v[8:11]
	v_mfma_f32_4x4x1_16b_f32 v[12:15], v48, v85, v[12:15]
	v_mfma_f32_4x4x1_16b_f32 v[16:19], v48, v93, v[16:19]
	v_mfma_f32_4x4x1_16b_f32 v[4:7], v29, v86, v[4:7]
	v_mfma_f32_4x4x1_16b_f32 v[8:11], v29, v94, v[8:11]
	v_mfma_f32_4x4x1_16b_f32 v[12:15], v33, v86, v[12:15]
	v_mfma_f32_4x4x1_16b_f32 v[16:19], v33, v94, v[16:19]
	v_mfma_f32_4x4x1_16b_f32 v[4:7], v45, v87, v[4:7]
	v_mfma_f32_4x4x1_16b_f32 v[8:11], v45, v95, v[8:11]
	v_mfma_f32_4x4x1_16b_f32 v[12:15], v49, v87, v[12:15]
	v_mfma_f32_4x4x1_16b_f32 v[16:19], v49, v95, v[16:19]
	v_mfma_f32_4x4x1_16b_f32 v[4:7], v30, v88, v[4:7]
	v_mfma_f32_4x4x1_16b_f32 v[8:11], v30, v96, v[8:11]
	v_mfma_f32_4x4x1_16b_f32 v[12:15], v34, v88, v[12:15]
	v_mfma_f32_4x4x1_16b_f32 v[16:19], v34, v96, v[16:19]
	v_mfma_f32_4x4x1_16b_f32 v[4:7], v46, v89, v[4:7]
	v_mfma_f32_4x4x1_16b_f32 v[8:11], v46, v97, v[8:11]
	v_mfma_f32_4x4x1_16b_f32 v[12:15], v50, v89, v[12:15]
	v_mfma_f32_4x4x1_16b_f32 v[16:19], v50, v97, v[16:19]
	v_mfma_f32_4x4x1_16b_f32 v[4:7], v31, v90, v[4:7]
	v_mfma_f32_4x4x1_16b_f32 v[8:11], v31, v98, v[8:11]
	v_mfma_f32_4x4x1_16b_f32 v[12:15], v35, v90, v[12:15]
	v_mfma_f32_4x4x1_16b_f32 v[16:19], v35, v98, v[16:19]
	v_mfma_f32_4x4x1_16b_f32 v[4:7], v47, v91, v[4:7]
	v_mfma_f32_4x4x1_16b_f32 v[8:11], v47, v99, v[8:11]
	v_mfma_f32_4x4x1_16b_f32 v[12:15], v51, v91, v[12:15]
	v_mfma_f32_4x4x1_16b_f32 v[16:19], v51, v99, v[16:19]
	s_add_i32 s36, s13, 7
	s_and_b32 s36, s36, 7
	s_lshl_b32 s1, s36, 13
	v_add_u32_e32 v118, s1, v117
	ds_read_b128 v[68:71], v118 offset:0
	ds_read_b128 v[72:75], v118 offset:1024
	ds_read_b128 v[76:79], v118 offset:2048
	ds_read_b128 v[80:83], v118 offset:3072
	s_waitcnt vmcnt(0)
	ds_write_b128 v3, v[136:139] offset:0
	ds_write_b128 v3, v[140:143] offset:1152
	ds_write_b128 v3, v[144:147] offset:2304
	ds_write_b128 v3, v[148:151] offset:3456
	s_waitcnt lgkmcnt(0)
	ds_read_b128 v[36:39], v116 offset:0
	ds_read_b128 v[40:43], v116 offset:2304
	ds_read_b128 v[44:47], v116 offset:256
	ds_read_b128 v[48:51], v116 offset:2560
	s_lshl_b32 s1, s36, 13
	s_add_u32 s1, s1, 0x1000
	v_add_u32_e32 v118, s1, v117
	ds_read_b128 v[84:87], v118 offset:0
	ds_read_b128 v[88:91], v118 offset:1024
	ds_read_b128 v[92:95], v118 offset:2048
	ds_read_b128 v[96:99], v118 offset:3072
	s_waitcnt lgkmcnt(6)
	v_lshlrev_b32_e32 v20, 16, v36
	v_and_b32_e32 v36, 0xffff0000, v36
	v_lshlrev_b32_e32 v21, 16, v37
	v_and_b32_e32 v37, 0xffff0000, v37
	v_lshlrev_b32_e32 v22, 16, v38
	v_and_b32_e32 v38, 0xffff0000, v38
	v_lshlrev_b32_e32 v23, 16, v39
	v_and_b32_e32 v39, 0xffff0000, v39
	v_lshlrev_b32_e32 v24, 16, v40
	v_and_b32_e32 v40, 0xffff0000, v40
	v_lshlrev_b32_e32 v25, 16, v41
	v_and_b32_e32 v41, 0xffff0000, v41
	v_lshlrev_b32_e32 v26, 16, v42
	v_and_b32_e32 v42, 0xffff0000, v42
	v_lshlrev_b32_e32 v27, 16, v43
	v_and_b32_e32 v43, 0xffff0000, v43
	v_mfma_f32_4x4x1_16b_f32 v[4:7], v20, v68, v[4:7]
	v_mfma_f32_4x4x1_16b_f32 v[8:11], v20, v76, v[8:11]
	s_waitcnt lgkmcnt(4)
	v_mfma_f32_4x4x1_16b_f32 v[12:15], v24, v68, v[12:15]
	v_lshlrev_b32_e32 v28, 16, v44
	v_mfma_f32_4x4x1_16b_f32 v[16:19], v24, v76, v[16:19]
	v_mfma_f32_4x4x1_16b_f32 v[4:7], v36, v69, v[4:7]
	v_and_b32_e32 v44, 0xffff0000, v44
	v_mfma_f32_4x4x1_16b_f32 v[8:11], v36, v77, v[8:11]
	v_mfma_f32_4x4x1_16b_f32 v[12:15], v40, v69, v[12:15]
	v_lshlrev_b32_e32 v29, 16, v45
	v_mfma_f32_4x4x1_16b_f32 v[16:19], v40, v77, v[16:19]
	v_mfma_f32_4x4x1_16b_f32 v[4:7], v21, v70, v[4:7]
	v_and_b32_e32 v45, 0xffff0000, v45
	v_mfma_f32_4x4x1_16b_f32 v[8:11], v21, v78, v[8:11]
	v_mfma_f32_4x4x1_16b_f32 v[12:15], v25, v70, v[12:15]
	v_lshlrev_b32_e32 v30, 16, v46
	v_mfma_f32_4x4x1_16b_f32 v[16:19], v25, v78, v[16:19]
	v_mfma_f32_4x4x1_16b_f32 v[4:7], v37, v71, v[4:7]
	v_and_b32_e32 v46, 0xffff0000, v46
	v_mfma_f32_4x4x1_16b_f32 v[8:11], v37, v79, v[8:11]
	v_mfma_f32_4x4x1_16b_f32 v[12:15], v41, v71, v[12:15]
	v_lshlrev_b32_e32 v31, 16, v47
	v_mfma_f32_4x4x1_16b_f32 v[16:19], v41, v79, v[16:19]
	v_mfma_f32_4x4x1_16b_f32 v[4:7], v22, v72, v[4:7]
	v_and_b32_e32 v47, 0xffff0000, v47
	v_mfma_f32_4x4x1_16b_f32 v[8:11], v22, v80, v[8:11]
	v_mfma_f32_4x4x1_16b_f32 v[12:15], v26, v72, v[12:15]
	v_lshlrev_b32_e32 v32, 16, v48
	v_mfma_f32_4x4x1_16b_f32 v[16:19], v26, v80, v[16:19]
	v_mfma_f32_4x4x1_16b_f32 v[4:7], v38, v73, v[4:7]
	v_and_b32_e32 v48, 0xffff0000, v48
	v_mfma_f32_4x4x1_16b_f32 v[8:11], v38, v81, v[8:11]
	v_mfma_f32_4x4x1_16b_f32 v[12:15], v42, v73, v[12:15]
	v_lshlrev_b32_e32 v33, 16, v49
	v_mfma_f32_4x4x1_16b_f32 v[16:19], v42, v81, v[16:19]
	v_mfma_f32_4x4x1_16b_f32 v[4:7], v23, v74, v[4:7]
	v_and_b32_e32 v49, 0xffff0000, v49
	v_mfma_f32_4x4x1_16b_f32 v[8:11], v23, v82, v[8:11]
	v_mfma_f32_4x4x1_16b_f32 v[12:15], v27, v74, v[12:15]
	v_lshlrev_b32_e32 v34, 16, v50
	v_mfma_f32_4x4x1_16b_f32 v[16:19], v27, v82, v[16:19]
	v_mfma_f32_4x4x1_16b_f32 v[4:7], v39, v75, v[4:7]
	v_and_b32_e32 v50, 0xffff0000, v50
	v_mfma_f32_4x4x1_16b_f32 v[8:11], v39, v83, v[8:11]
	v_mfma_f32_4x4x1_16b_f32 v[12:15], v43, v75, v[12:15]
	v_lshlrev_b32_e32 v35, 16, v51
	v_mfma_f32_4x4x1_16b_f32 v[16:19], v43, v83, v[16:19]
	s_waitcnt lgkmcnt(0)
; __device__ __forceinline__ float rs_from_ss(float ss) { return rsqrtf(ss * (1.0f / DM) + RMS_EPS); }
; __global__ void __launch_bounds__(NWAVES * 64, 2) fwd_megakernel(Args args) {
;     ...
;                 for (int q = 0; q < 4; ++q) { float d = 0.f;
; #pragma unroll
;                     for (int jj = 0; jj < 4; ++jj) { const u32x4 w = pw[q][jj];
;                         d += __uint_as_float(w.x << 16) * wreg[8 * jj + 0] + __uint_as_float(w.x & 0xffff0000u) * wreg[8 * jj + 1] + __uint_as_float(w.y << 16) * wreg[8 * jj + 2] + __uint_as_float(w.y & 0xffff0000u) * wreg[8 * jj + 3]
;                            + __uint_as_float(w.z << 16) * wreg[8 * jj + 4] + __uint_as_float(w.z & 0xffff0000u) * wreg[8 * jj + 5] + __uint_as_float(w.w << 16) * wreg[8 * jj + 6] + __uint_as_float(w.w & 0xffff0000u) * wreg[8 * jj + 7]; }
;                     d = wave_sum(d);
;                     if (ln == 0) { const int m = m0 + q; const float f = d * rs_from_ss(sq[q]) + bf; const float lf = fminf(f, 0.f) - log1pf(__expf(-fabsf(f)));
;                         logfb[((size_t)(m / SEQ) * NH + wave) * SEQ + (m % SEQ)] = lf; } }
	v_mfma_f32_4x4x1_16b_f32 v[4:7], v28, v84, v[4:7]
	v_mfma_f32_4x4x1_16b_f32 v[8:11], v28, v92, v[8:11]
	v_mfma_f32_4x4x1_16b_f32 v[12:15], v32, v84, v[12:15]
	v_mfma_f32_4x4x1_16b_f32 v[16:19], v32, v92, v[16:19]
	v_mfma_f32_4x4x1_16b_f32 v[4:7], v44, v85, v[4:7]
	v_mfma_f32_4x4x1_16b_f32 v[8:11], v44, v93, v[8:11]
	v_mfma_f32_4x4x1_16b_f32 v[12:15], v48, v85, v[12:15]
	v_mfma_f32_4x4x1_16b_f32 v[16:19], v48, v93, v[16:19]
	v_mfma_f32_4x4x1_16b_f32 v[4:7], v29, v86, v[4:7]
	v_mfma_f32_4x4x1_16b_f32 v[8:11], v29, v94, v[8:11]
	v_mfma_f32_4x4x1_16b_f32 v[12:15], v33, v86, v[12:15]
	v_mfma_f32_4x4x1_16b_f32 v[16:19], v33, v94, v[16:19]
	v_mfma_f32_4x4x1_16b_f32 v[4:7], v45, v87, v[4:7]
	v_mfma_f32_4x4x1_16b_f32 v[8:11], v45, v95, v[8:11]
	v_mfma_f32_4x4x1_16b_f32 v[12:15], v49, v87, v[12:15]
	v_mfma_f32_4x4x1_16b_f32 v[16:19], v49, v95, v[16:19]
	v_mfma_f32_4x4x1_16b_f32 v[4:7], v30, v88, v[4:7]
	v_mfma_f32_4x4x1_16b_f32 v[8:11], v30, v96, v[8:11]
	v_mfma_f32_4x4x1_16b_f32 v[12:15], v34, v88, v[12:15]
	v_mfma_f32_4x4x1_16b_f32 v[16:19], v34, v96, v[16:19]
	v_mfma_f32_4x4x1_16b_f32 v[4:7], v46, v89, v[4:7]
	v_mfma_f32_4x4x1_16b_f32 v[8:11], v46, v97, v[8:11]
	v_mfma_f32_4x4x1_16b_f32 v[12:15], v50, v89, v[12:15]
	v_mfma_f32_4x4x1_16b_f32 v[16:19], v50, v97, v[16:19]
	v_mfma_f32_4x4x1_16b_f32 v[4:7], v31, v90, v[4:7]
	v_mfma_f32_4x4x1_16b_f32 v[8:11], v31, v98, v[8:11]
	v_mfma_f32_4x4x1_16b_f32 v[12:15], v35, v90, v[12:15]
	v_mfma_f32_4x4x1_16b_f32 v[16:19], v35, v98, v[16:19]
	v_mfma_f32_4x4x1_16b_f32 v[4:7], v47, v91, v[4:7]
	v_mfma_f32_4x4x1_16b_f32 v[8:11], v47, v99, v[8:11]
	v_mfma_f32_4x4x1_16b_f32 v[12:15], v51, v91, v[12:15]
	v_mfma_f32_4x4x1_16b_f32 v[16:19], v51, v99, v[16:19]
	v_lshrrev_b32_e32 v20, 3, v168
	v_and_b32_e32 v21, 7, v168
	v_lshlrev_b32_e32 v22, 2, v20
	v_lshlrev_b32_e32 v23, 2, v21
	s_lshl_b32 s5, s12, 3
	s_add_u32 s5, s5, s4
	s_lshl_b32 s1, s5, 2
	s_add_u32 s1, s1, 0x10000
	s_add_u32 s8, s60, s1
	s_addc_u32 s9, s61, 0
	global_load_dword v24, v22, s[8:9]
	global_load_dword v25, v23, s[16:17]
	s_mul_i32 s1, s12, 0x1200
	s_add_u32 s1, s1, 0x10000
	v_lshlrev_b32_e32 v26, 2, v168
	v_add_u32_e32 v26, s1, v26
	s_nop 7
	ds_write_b32 v26, v4 offset:0
	ds_write_b32 v26, v5 offset:256
	ds_write_b32 v26, v6 offset:512
	ds_write_b32 v26, v7 offset:768
	ds_write_b32 v26, v8 offset:1024
	ds_write_b32 v26, v9 offset:1280
	ds_write_b32 v26, v10 offset:1536
	ds_write_b32 v26, v11 offset:1792
	ds_write_b32 v26, v12 offset:2048
	ds_write_b32 v26, v13 offset:2304
	ds_write_b32 v26, v14 offset:2560
	ds_write_b32 v26, v15 offset:2816
	ds_write_b32 v26, v16 offset:3072
	ds_write_b32 v26, v17 offset:3328
	ds_write_b32 v26, v18 offset:3584
	ds_write_b32 v26, v19 offset:3840
	v_lshrrev_b32_e32 v27, 2, v20
	v_lshrrev_b32_e32 v28, 2, v21
	v_lshl_or_b32 v27, v27, 1, v28
	v_and_b32_e32 v28, 3, v20
	v_lshl_or_b32 v27, v27, 2, v28
	v_and_b32_e32 v28, 3, v21
	v_lshlrev_b32_e32 v28, 2, v28
	v_lshl_or_b32 v27, v27, 8, v28
	v_add_u32_e32 v27, s1, v27
	s_waitcnt lgkmcnt(0)
	ds_read_b32 v36, v27 offset:0
	ds_read_b32 v37, v27 offset:16
	ds_read_b32 v38, v27 offset:32
	ds_read_b32 v39, v27 offset:48
	ds_read_b32 v40, v27 offset:64
	ds_read_b32 v41, v27 offset:80
	ds_read_b32 v42, v27 offset:96
	ds_read_b32 v43, v27 offset:112
	ds_read_b32 v44, v27 offset:128
	ds_read_b32 v45, v27 offset:144
	ds_read_b32 v46, v27 offset:160
	ds_read_b32 v47, v27 offset:176
	ds_read_b32 v48, v27 offset:192
	ds_read_b32 v49, v27 offset:208
	ds_read_b32 v50, v27 offset:224
	ds_read_b32 v51, v27 offset:240
	s_lshr_b32 s1, s5, 11
	s_lshl_b32 s1, s1, 16
	s_and_b32 s5, s5, 0x7ff
	s_lshl_b32 s5, s5, 2
	s_add_u32 s1, s1, s5
	s_add_u32 s1, s1, 0x80000
	s_add_u32 s8, s60, s1
	s_addc_u32 s9, s61, 0
	v_lshl_or_b32 v29, v21, 13, v22
	s_waitcnt lgkmcnt(0)
	v_add_f32_e32 v36, v36, v44
	v_add_f32_e32 v37, v37, v45
	v_add_f32_e32 v38, v38, v46
	v_add_f32_e32 v39, v39, v47
	v_add_f32_e32 v40, v40, v48
	v_add_f32_e32 v41, v41, v49
	v_add_f32_e32 v42, v42, v50
	v_add_f32_e32 v43, v43, v51
	v_add_f32_e32 v36, v36, v40
	v_add_f32_e32 v37, v37, v41
	v_add_f32_e32 v38, v38, v42
	v_add_f32_e32 v39, v39, v43
	v_add_f32_e32 v36, v36, v38
	v_add_f32_e32 v37, v37, v39
	v_add_f32_e32 v36, v36, v37
	s_waitcnt vmcnt(0)
	v_fmamk_f32 v24, v24, 0x3a000000, v172
	v_rsq_f32_e32 v24, v24
	s_nop 0
	v_fma_f32 v30, v36, v24, v25
	v_mul_f32_e64 v31, |v30|, s18
	v_exp_f32_e32 v31, v31
	s_nop 0
	v_add_f32_e32 v32, 1.0, v31
	v_add_f32_e32 v33, -1.0, v32
	v_sub_f32_e32 v33, v33, v31
	v_log_f32_e32 v34, v32
	v_rcp_f32_e32 v35, v32
	v_mov_b32_e32 v37, 0x3eaaaaab
	v_fmac_f32_e32 v37, 0xbe800000, v31
	v_mul_f32_e32 v34, s19, v34
	v_fma_f32 v34, -v33, v35, v34
	v_fma_f32 v37, v31, v37, -0.5
	v_fma_f32 v37, v31, v37, 1.0
	v_mul_f32_e32 v37, v31, v37
	v_cmp_gt_f32_e32 vcc, 0x3c800000, v31
	v_min_f32_e32 v38, 0, v30
	s_nop 0
	v_cndmask_b32_e32 v34, v34, v37, vcc
	v_sub_f32_e32 v38, v38, v34
	global_store_dword v29, v38, s[8:9]
	s_lshl_b32 s5, s21, 4
	s_add_i32 s4, s4, s5
	s_cmpk_gt_i32 s4, 0x3fff
	s_cbranch_scc0 .Llg_trip
	s_waitcnt lgkmcnt(0)
	s_barrier
